# in-proj and FF1 K-loops: the four LDS fragment-read base addresses are computed once per tile instead of every iteration
# speedup vs baseline: 1.0031x; 1.0031x over previous
; #define PG8_STAGE(bufoff, gbase, voff) do { _Pragma("unroll") for (int _i = 0; _i < 2; ++_i) \
;         __builtin_amdgcn_global_load_lds((const unsigned*)((const char*)(gbase) + (voff)[_i]), (LAS unsigned*)(lds + (bufoff) + ldsw + _i * 8192), 16, 0, 0); } while (0)
; #define PG8_LDA(dst, b, h) do { _Pragma("unroll") for (int m = 0; m < 4; ++m) _Pragma("unroll") for (int k = 0; k < 2; ++k) dst[m][k] = *(const LAS bf16x8*)(lds + PG8_SA(b, h) + aoff + m * 2048 + k * 1024); } while (0)
; template <class Epi, class Sched>
; __device__ __forceinline__ void gemm_phase(LAS unsigned char* lds, const Gemm g, const Sched& S, const Epi& E) {
;     ...
;     f32x4 acc[2][2][4][2];
; #pragma unroll
;     for (int a = 0; a < 2; ++a)
; #pragma unroll
;         for (int b = 0; b < 2; ++b)
; #pragma unroll
;             for (int m = 0; m < 4; ++m)
; #pragma unroll
;                 for (int n = 0; n < 2; ++n) acc[a][b][m][n] = (f32x4){0.f, 0.f, 0.f, 0.f};
;     bf16x8 At[4][2], B0[2][2], B1[2][2];
;     const char* cA = (const char*)g.A + (size_t)cur.pm * tstep; const char* cB = (const char*)g.Bt + (size_t)cur.pn * tstep;
;     S.a_ready(cur);
;     PG8_STAGE(PG8_SB(0, 0), cB, voffB); PG8_STAGE(PG8_SA(0, 0), cA, voffA); PG8_STAGE(PG8_SB(0, 1), cB + hstep, voffB); PG8_STAGE(PG8_SA(0, 1), cA + hstep, voffA);
;     if (wr == 1) PG8_BAR;
;     PG8_WAIT_V(4); PG8_BAR;
;     PG8_STAGE(PG8_SB(1, 0), cB + kstep, voffB); PG8_STAGE(PG8_SA(1, 0), cA + kstep, voffA); PG8_STAGE(PG8_SB(1, 1), cB + hstep + kstep, voffB);
;     PG8_WAIT_V(6); PG8_BAR;
;     for (;;) {
;         const bool has_next = S.next(ui + 1, nxt);
;         const char* nA = has_next ? (const char*)g.A + (size_t)nxt.pm * tstep : cA; const char* nB = has_next ? (const char*)g.Bt + (size_t)nxt.pn * tstep : cB;
;         for (int t = 0; t < nt; t += 2) {
;             const bool last = (t == nt - 2);
;             const char* a1 = cA + (size_t)(t + 1) * kstep;
;             const char* a2 = last ? nA : cA + (size_t)(t + 2) * kstep; const char* b2 = last ? nB : cB + (size_t)(t + 2) * kstep;
;             const char* a3 = a2 + kstep; const char* b3 = b2 + kstep;
;             if (last && has_next) S.a_ready(nxt);
;             PG8_LDB(B0, 0, 0); PG8_SCHED; PG8_LDA(At, 0, 0); PG8_STAGE(PG8_SA(1, 1), a1 + hstep, voffA);
;             PG8_WAIT_L(8); PG8_BAR; PG8_WAIT_L(0); PG8_MMA(0, 0, At, B0); PG8_BAR; PG8_SCHED;
.LBB0_341:
	v_mov_b64_e32 v[2:3], 0x7e0
	s_ashr_i32 s11, s10, 31
	v_cmp_lt_i64_e32 vcc, s[12:13], v[2:3]
	s_lshl_b64 s[12:13], s[10:11], 20
	s_add_u32 s12, s56, s12
	s_addc_u32 s13, s57, s13
	s_and_b64 s[14:15], vcc, exec
	s_cselect_b32 s11, s13, s17
	s_cselect_b32 s34, s12, s16
	s_ashr_i32 s9, s8, 31
	s_lshl_b64 s[14:15], s[8:9], 20
	v_readlane_b32 s9, v254, 10
	s_add_u32 s14, s9, s14
	v_readlane_b32 s9, v254, 11
	s_addc_u32 s15, s9, s15
	s_and_b64 s[20:21], vcc, exec
	s_cselect_b32 s9, s15, s19
	s_cselect_b32 s35, s14, s18
	s_add_u32 s16, s16, 0x80080
	s_addc_u32 s17, s17, 0
	s_add_u32 s36, s18, 0x100
	v_mov_b32_e32 v2, 0
	s_addc_u32 s37, s19, 0
	s_mov_b32 s38, -2
	v_mov_b32_e32 v3, v2
	v_mov_b32_e32 v4, v2
	v_mov_b32_e32 v5, v2
	v_mov_b32_e32 v6, v2
	v_mov_b32_e32 v7, v2
	v_mov_b32_e32 v8, v2
	v_mov_b32_e32 v9, v2
	v_mov_b32_e32 v14, v2
	v_mov_b32_e32 v15, v2
	v_mov_b32_e32 v16, v2
	v_mov_b32_e32 v17, v2
	v_mov_b32_e32 v22, v2
	v_mov_b32_e32 v23, v2
	v_mov_b32_e32 v24, v2
	v_mov_b32_e32 v25, v2
	v_mov_b32_e32 v30, v2
	v_mov_b32_e32 v31, v2
	v_mov_b32_e32 v32, v2
	v_mov_b32_e32 v33, v2
	v_mov_b32_e32 v38, v2
	v_mov_b32_e32 v39, v2
	v_mov_b32_e32 v40, v2
	v_mov_b32_e32 v41, v2
	v_mov_b32_e32 v46, v2
	v_mov_b32_e32 v47, v2
	v_mov_b32_e32 v48, v2
	v_mov_b32_e32 v49, v2
	v_mov_b32_e32 v54, v2
	v_mov_b32_e32 v55, v2
	v_mov_b32_e32 v56, v2
	v_mov_b32_e32 v57, v2
	v_mov_b32_e32 v10, v2
	v_mov_b32_e32 v11, v2
	v_mov_b32_e32 v12, v2
	v_mov_b32_e32 v13, v2
	v_mov_b32_e32 v18, v2
	v_mov_b32_e32 v19, v2
	v_mov_b32_e32 v20, v2
	v_mov_b32_e32 v21, v2
	v_mov_b32_e32 v26, v2
	v_mov_b32_e32 v27, v2
	v_mov_b32_e32 v28, v2
	v_mov_b32_e32 v29, v2
	v_mov_b32_e32 v34, v2
	v_mov_b32_e32 v35, v2
	v_mov_b32_e32 v36, v2
	v_mov_b32_e32 v37, v2
	v_mov_b32_e32 v42, v2
	v_mov_b32_e32 v43, v2
	v_mov_b32_e32 v44, v2
	v_mov_b32_e32 v45, v2
	v_mov_b32_e32 v50, v2
	v_mov_b32_e32 v51, v2
	v_mov_b32_e32 v52, v2
	v_mov_b32_e32 v53, v2
	v_mov_b32_e32 v58, v2
	v_mov_b32_e32 v59, v2
	v_mov_b32_e32 v60, v2
	v_mov_b32_e32 v61, v2
	v_mov_b32_e32 v62, v2
	v_mov_b32_e32 v63, v2
	v_mov_b32_e32 v64, v2
	v_mov_b32_e32 v65, v2
	v_mov_b32_e32 v66, v2
	v_mov_b32_e32 v67, v2
	v_mov_b32_e32 v68, v2
	v_mov_b32_e32 v69, v2
	v_mov_b32_e32 v70, v2
	v_mov_b32_e32 v71, v2
	v_mov_b32_e32 v72, v2
	v_mov_b32_e32 v73, v2
	v_mov_b32_e32 v78, v2
	v_mov_b32_e32 v79, v2
	v_mov_b32_e32 v80, v2
	v_mov_b32_e32 v81, v2
	v_mov_b32_e32 v86, v2
	v_mov_b32_e32 v87, v2
	v_mov_b32_e32 v88, v2
	v_mov_b32_e32 v89, v2
	v_mov_b32_e32 v94, v2
	v_mov_b32_e32 v95, v2
	v_mov_b32_e32 v96, v2
	v_mov_b32_e32 v97, v2
	v_mov_b32_e32 v102, v2
	v_mov_b32_e32 v103, v2
	v_mov_b32_e32 v104, v2
	v_mov_b32_e32 v105, v2
	v_mov_b32_e32 v110, v2
	v_mov_b32_e32 v111, v2
	v_mov_b32_e32 v112, v2
	v_mov_b32_e32 v113, v2
	v_mov_b32_e32 v118, v2
	v_mov_b32_e32 v119, v2
	v_mov_b32_e32 v120, v2
	v_mov_b32_e32 v121, v2
	v_mov_b32_e32 v74, v2
	v_mov_b32_e32 v75, v2
	v_mov_b32_e32 v76, v2
	v_mov_b32_e32 v77, v2
	v_mov_b32_e32 v82, v2
	v_mov_b32_e32 v83, v2
	v_mov_b32_e32 v84, v2
	v_mov_b32_e32 v85, v2
	v_mov_b32_e32 v90, v2
	v_mov_b32_e32 v91, v2
	v_mov_b32_e32 v92, v2
	v_mov_b32_e32 v93, v2
	v_mov_b32_e32 v98, v2
	v_mov_b32_e32 v99, v2
	v_mov_b32_e32 v100, v2
	v_mov_b32_e32 v101, v2
	v_mov_b32_e32 v106, v2
	v_mov_b32_e32 v107, v2
	v_mov_b32_e32 v108, v2
	v_mov_b32_e32 v109, v2
	v_mov_b32_e32 v114, v2
	v_mov_b32_e32 v115, v2
	v_mov_b32_e32 v116, v2
	v_mov_b32_e32 v117, v2
	v_mov_b32_e32 v122, v2
	v_mov_b32_e32 v123, v2
	v_mov_b32_e32 v124, v2
	v_mov_b32_e32 v125, v2
	v_mov_b32_e32 v126, v2
	v_mov_b32_e32 v127, v2
	v_mov_b32_e32 v128, v2
	v_mov_b32_e32 v129, v2
	v_readlane_b32 s42, v253, 6
	s_mov_b64 s[44:45], 0x80
	v_add_u32_e32 v211, 0x14000, v147
	v_add_u32_e32 v220, 0x18000, v147
	v_add_u32_e32 v221, 0x1c000, v147
	v_add_u32_e32 v210, s42, v147
.LBB0_342:
	s_nop 0
	ds_read_b128 v[142:145], v210
	ds_read_b128 v[150:153], v210 offset:1024
	ds_read_b128 v[154:157], v210 offset:2048
	ds_read_b128 v[158:161], v210 offset:3072
	s_add_u32 s18, s16, 0xfff80080
	s_addc_u32 s19, s17, -1
	s_cmp_eq_u32 s38, 28
	s_cselect_b32 s21, s11, s19
	s_cselect_b32 s20, s34, s18
	s_cselect_b32 s19, s9, s37
	s_cselect_b32 s18, s35, s36
	s_add_i32 m0, s24, 0xc000
	ds_read_b128 v[162:165], v149
	ds_read_b128 v[166:169], v149 offset:1024
	ds_read_b128 v[170:173], v149 offset:2048
	ds_read_b128 v[174:177], v149 offset:3072
	ds_read_b128 v[178:181], v149 offset:4096
	ds_read_b128 v[182:185], v149 offset:5120
	ds_read_b128 v[186:189], v149 offset:6144
	ds_read_b128 v[190:193], v149 offset:7168
	global_load_lds_dwordx4 v138, s[16:17]
	s_add_i32 m0, s24, 0xe000
	s_nop 0
	global_load_lds_dwordx4 v140, s[16:17]
	s_waitcnt lgkmcnt(8)
	s_barrier
	s_waitcnt lgkmcnt(0)
	v_mfma_f32_16x16x32_bf16 v[126:129], v[142:145], v[162:165], v[126:129]
	v_mfma_f32_16x16x32_bf16 v[122:125], v[154:157], v[162:165], v[122:125]
	v_mfma_f32_16x16x32_bf16 v[114:117], v[142:145], v[170:173], v[114:117]
	v_mfma_f32_16x16x32_bf16 v[106:109], v[154:157], v[170:173], v[106:109]
	v_mfma_f32_16x16x32_bf16 v[98:101], v[142:145], v[178:181], v[98:101]
	v_mfma_f32_16x16x32_bf16 v[90:93], v[154:157], v[178:181], v[90:93]
	v_mfma_f32_16x16x32_bf16 v[82:85], v[142:145], v[186:189], v[82:85]
	v_mfma_f32_16x16x32_bf16 v[74:77], v[154:157], v[186:189], v[74:77]
	v_mfma_f32_16x16x32_bf16 v[126:129], v[150:153], v[166:169], v[126:129]
	v_mfma_f32_16x16x32_bf16 v[122:125], v[158:161], v[166:169], v[122:125]
	v_mfma_f32_16x16x32_bf16 v[114:117], v[150:153], v[174:177], v[114:117]
	v_mfma_f32_16x16x32_bf16 v[106:109], v[158:161], v[174:177], v[106:109]
	v_mfma_f32_16x16x32_bf16 v[98:101], v[150:153], v[182:185], v[98:101]
	v_mfma_f32_16x16x32_bf16 v[90:93], v[158:161], v[182:185], v[90:93]
	v_mfma_f32_16x16x32_bf16 v[82:85], v[150:153], v[190:193], v[82:85]
	v_mfma_f32_16x16x32_bf16 v[74:77], v[158:161], v[190:193], v[74:77]
	s_barrier
; #define PG8_STAGE(bufoff, gbase, voff) do { _Pragma("unroll") for (int _i = 0; _i < 2; ++_i) \
;         __builtin_amdgcn_global_load_lds((const unsigned*)((const char*)(gbase) + (voff)[_i]), (LAS unsigned*)(lds + (bufoff) + ldsw + _i * 8192), 16, 0, 0); } while (0)
; #define PG8_LDA(dst, b, h) do { _Pragma("unroll") for (int m = 0; m < 4; ++m) _Pragma("unroll") for (int k = 0; k < 2; ++k) dst[m][k] = *(const LAS bf16x8*)(lds + PG8_SA(b, h) + aoff + m * 2048 + k * 1024); } while (0)
; #define PG8_LDB(dst, b, h) do { _Pragma("unroll") for (int n = 0; n < 2; ++n) _Pragma("unroll") for (int k = 0; k < 2; ++k) dst[n][k] = *(const LAS bf16x8*)(lds + PG8_SB(b, h) + boff + n * 2048 + k * 1024); } while (0)
; #define PG8_MMA(ai, bj, At, Bt) do { __builtin_amdgcn_s_setprio(1); _Pragma("unroll") for (int m = 0; m < 4; ++m) _Pragma("unroll") for (int n = 0; n < 2; ++n) _Pragma("unroll") for (int k = 0; k < 2; ++k) \
;         acc[ai][bj][m][n] = __builtin_amdgcn_mfma_f32_16x16x32_bf16(Bt[n][k], At[m][k], acc[ai][bj][m][n], 0, 0, 0); __builtin_amdgcn_s_setprio(0); } while (0)
; #define PG8_WAIT_V(n) asm volatile("s_waitcnt vmcnt(" #n ")" ::: "memory")
; #define PG8_WAIT_L(n) asm volatile("s_waitcnt lgkmcnt(" #n ")" ::: "memory")
; #define PG8_BAR __builtin_amdgcn_s_barrier()
; #define PG8_SCHED __builtin_amdgcn_sched_barrier(0)
; template <class Epi, class Sched>
; __device__ __forceinline__ void gemm_phase(LAS unsigned char* lds, const Gemm g, const Sched& S, const Epi& E) {
;     ...
;             PG8_WAIT_L(8); PG8_BAR; PG8_WAIT_L(0); PG8_MMA(0, 0, At, B0); PG8_BAR; PG8_SCHED;
;             PG8_LDB(B1, 0, 1); PG8_STAGE(PG8_SB(0, 0), b2, voffB);
;             PG8_BAR; PG8_WAIT_L(0); PG8_MMA(0, 1, At, B1); PG8_BAR;
;             PG8_LDA(At, 0, 1); PG8_STAGE(PG8_SA(0, 0), a2, voffA);
;             PG8_BAR; PG8_WAIT_L(0); PG8_MMA(1, 0, At, B0); PG8_BAR; PG8_SCHED;
;             PG8_STAGE(PG8_SB(0, 1), b2 + hstep, voffB);
;             PG8_WAIT_V(6); PG8_BAR; PG8_MMA(1, 1, At, B1); PG8_BAR;
;             PG8_LDB(B0, 1, 0); PG8_SCHED; PG8_LDA(At, 1, 0); PG8_STAGE(PG8_SA(0, 1), a2 + hstep, voffA);
;             PG8_WAIT_L(8); PG8_BAR; PG8_WAIT_L(0); PG8_MMA(0, 0, At, B0); PG8_BAR; PG8_SCHED;
	s_add_i32 s39, 0, 0x14000
	s_add_i32 s40, s42, s23
	s_mov_b32 m0, s40
	ds_read_b128 v[194:197], v211
	ds_read_b128 v[198:201], v211 offset:1024
	ds_read_b128 v[202:205], v211 offset:2048
	ds_read_b128 v[206:209], v211 offset:3072
	global_load_lds_dwordx4 v0, s[18:19]
	s_add_i32 m0, s40, 0x2000
	s_nop 0
	global_load_lds_dwordx4 v130, s[18:19]
	s_barrier
	s_waitcnt lgkmcnt(0)
	v_mfma_f32_16x16x32_bf16 v[118:121], v[194:197], v[162:165], v[118:121]
	v_mfma_f32_16x16x32_bf16 v[110:113], v[202:205], v[162:165], v[110:113]
	v_mfma_f32_16x16x32_bf16 v[102:105], v[194:197], v[170:173], v[102:105]
	v_mfma_f32_16x16x32_bf16 v[94:97], v[202:205], v[170:173], v[94:97]
	v_mfma_f32_16x16x32_bf16 v[86:89], v[194:197], v[178:181], v[86:89]
	v_mfma_f32_16x16x32_bf16 v[78:81], v[202:205], v[178:181], v[78:81]
	v_mfma_f32_16x16x32_bf16 v[70:73], v[194:197], v[186:189], v[70:73]
	v_mfma_f32_16x16x32_bf16 v[66:69], v[202:205], v[186:189], v[66:69]
	v_mfma_f32_16x16x32_bf16 v[118:121], v[198:201], v[166:169], v[118:121]
	v_mfma_f32_16x16x32_bf16 v[110:113], v[206:209], v[166:169], v[110:113]
	v_mfma_f32_16x16x32_bf16 v[102:105], v[198:201], v[174:177], v[102:105]
	v_mfma_f32_16x16x32_bf16 v[94:97], v[206:209], v[174:177], v[94:97]
	v_mfma_f32_16x16x32_bf16 v[86:89], v[198:201], v[182:185], v[86:89]
	v_mfma_f32_16x16x32_bf16 v[78:81], v[206:209], v[182:185], v[78:81]
	v_mfma_f32_16x16x32_bf16 v[70:73], v[198:201], v[190:193], v[70:73]
	v_mfma_f32_16x16x32_bf16 v[66:69], v[206:209], v[190:193], v[66:69]
	s_mov_b32 m0, s24
	s_add_u32 s44, s20, 0x80
	s_addc_u32 s45, s21, 0
	s_barrier
	ds_read_b128 v[162:165], v149 offset:16384
	ds_read_b128 v[166:169], v149 offset:17408
	ds_read_b128 v[170:173], v149 offset:18432
	ds_read_b128 v[174:177], v149 offset:19456
	ds_read_b128 v[178:181], v149 offset:20480
	ds_read_b128 v[182:185], v149 offset:21504
	ds_read_b128 v[186:189], v149 offset:22528
	ds_read_b128 v[190:193], v149 offset:23552
	global_load_lds_dwordx4 v134, s[20:21]
	s_mov_b32 m0, s25
	s_nop 0
	global_load_lds_dwordx4 v132, s[20:21]
	s_barrier
	s_waitcnt lgkmcnt(0)
	v_mfma_f32_16x16x32_bf16 v[62:65], v[142:145], v[162:165], v[62:65]
	v_mfma_f32_16x16x32_bf16 v[58:61], v[154:157], v[162:165], v[58:61]
	v_mfma_f32_16x16x32_bf16 v[50:53], v[142:145], v[170:173], v[50:53]
	v_mfma_f32_16x16x32_bf16 v[42:45], v[154:157], v[170:173], v[42:45]
	v_mfma_f32_16x16x32_bf16 v[34:37], v[142:145], v[178:181], v[34:37]
	v_mfma_f32_16x16x32_bf16 v[26:29], v[154:157], v[178:181], v[26:29]
	v_mfma_f32_16x16x32_bf16 v[18:21], v[142:145], v[186:189], v[18:21]
	v_mfma_f32_16x16x32_bf16 v[10:13], v[154:157], v[186:189], v[10:13]
	v_mfma_f32_16x16x32_bf16 v[62:65], v[150:153], v[166:169], v[62:65]
	v_mfma_f32_16x16x32_bf16 v[58:61], v[158:161], v[166:169], v[58:61]
	v_mfma_f32_16x16x32_bf16 v[50:53], v[150:153], v[174:177], v[50:53]
	v_mfma_f32_16x16x32_bf16 v[42:45], v[158:161], v[174:177], v[42:45]
	v_mfma_f32_16x16x32_bf16 v[34:37], v[150:153], v[182:185], v[34:37]
	v_mfma_f32_16x16x32_bf16 v[26:29], v[158:161], v[182:185], v[26:29]
	v_mfma_f32_16x16x32_bf16 v[18:21], v[150:153], v[190:193], v[18:21]
	v_mfma_f32_16x16x32_bf16 v[10:13], v[158:161], v[190:193], v[10:13]
	s_barrier
	s_add_u32 s40, s18, 0x80000
	s_addc_u32 s41, s19, 0
	s_add_i32 s39, s39, s23
	s_mov_b32 m0, s39
	s_nop 0
	global_load_lds_dwordx4 v0, s[40:41]
	s_add_i32 m0, s39, 0x2000
	s_nop 0
	global_load_lds_dwordx4 v130, s[40:41]
	s_waitcnt vmcnt(6)
	s_barrier
	v_mfma_f32_16x16x32_bf16 v[54:57], v[194:197], v[162:165], v[54:57]
	v_mfma_f32_16x16x32_bf16 v[46:49], v[202:205], v[162:165], v[46:49]
	v_mfma_f32_16x16x32_bf16 v[38:41], v[194:197], v[170:173], v[38:41]
	v_mfma_f32_16x16x32_bf16 v[30:33], v[202:205], v[170:173], v[30:33]
	v_mfma_f32_16x16x32_bf16 v[22:25], v[194:197], v[178:181], v[22:25]
	v_mfma_f32_16x16x32_bf16 v[14:17], v[202:205], v[178:181], v[14:17]
	v_mfma_f32_16x16x32_bf16 v[6:9], v[194:197], v[186:189], v[6:9]
	v_mfma_f32_16x16x32_bf16 v[2:5], v[202:205], v[186:189], v[2:5]
	v_mfma_f32_16x16x32_bf16 v[54:57], v[198:201], v[166:169], v[54:57]
	v_mfma_f32_16x16x32_bf16 v[46:49], v[206:209], v[166:169], v[46:49]
	v_mfma_f32_16x16x32_bf16 v[38:41], v[198:201], v[174:177], v[38:41]
	v_mfma_f32_16x16x32_bf16 v[30:33], v[206:209], v[174:177], v[30:33]
	v_mfma_f32_16x16x32_bf16 v[22:25], v[198:201], v[182:185], v[22:25]
	v_mfma_f32_16x16x32_bf16 v[14:17], v[206:209], v[182:185], v[14:17]
	v_mfma_f32_16x16x32_bf16 v[6:9], v[198:201], v[190:193], v[6:9]
	v_mfma_f32_16x16x32_bf16 v[2:5], v[206:209], v[190:193], v[2:5]
	s_add_i32 s39, 0, 0x18000
	s_barrier
	ds_read_b128 v[142:145], v220
	ds_read_b128 v[150:153], v220 offset:1024
	ds_read_b128 v[154:157], v220 offset:2048
	ds_read_b128 v[158:161], v220 offset:3072
	s_add_u32 s20, s20, 0x80000
	s_addc_u32 s21, s21, 0
	s_mov_b32 m0, s26
	ds_read_b128 v[162:165], v149 offset:32768
	ds_read_b128 v[166:169], v149 offset:33792
	ds_read_b128 v[170:173], v149 offset:34816
	ds_read_b128 v[174:177], v149 offset:35840
	ds_read_b128 v[178:181], v149 offset:36864
	ds_read_b128 v[182:185], v149 offset:37888
	ds_read_b128 v[186:189], v149 offset:38912
	ds_read_b128 v[190:193], v149 offset:39936
	global_load_lds_dwordx4 v134, s[20:21]
	s_mov_b32 m0, s27
	s_nop 0
	global_load_lds_dwordx4 v132, s[20:21]
	s_waitcnt lgkmcnt(8)
	s_barrier
; #define PG8_STAGE(bufoff, gbase, voff) do { _Pragma("unroll") for (int _i = 0; _i < 2; ++_i) \
;         __builtin_amdgcn_global_load_lds((const unsigned*)((const char*)(gbase) + (voff)[_i]), (LAS unsigned*)(lds + (bufoff) + ldsw + _i * 8192), 16, 0, 0); } while (0)
; #define PG8_LDA(dst, b, h) do { _Pragma("unroll") for (int m = 0; m < 4; ++m) _Pragma("unroll") for (int k = 0; k < 2; ++k) dst[m][k] = *(const LAS bf16x8*)(lds + PG8_SA(b, h) + aoff + m * 2048 + k * 1024); } while (0)
; #define PG8_LDB(dst, b, h) do { _Pragma("unroll") for (int n = 0; n < 2; ++n) _Pragma("unroll") for (int k = 0; k < 2; ++k) dst[n][k] = *(const LAS bf16x8*)(lds + PG8_SB(b, h) + boff + n * 2048 + k * 1024); } while (0)
; #define PG8_BAR __builtin_amdgcn_s_barrier()
; template <class Epi, class Sched>
; __device__ __forceinline__ void gemm_phase(LAS unsigned char* lds, const Gemm g, const Sched& S, const Epi& E) {
;     ...
;             PG8_WAIT_L(8); PG8_BAR; PG8_WAIT_L(0); PG8_MMA(0, 0, At, B0); PG8_BAR; PG8_SCHED;
;             PG8_LDB(B1, 1, 1); PG8_STAGE(PG8_SB(1, 0), b3, voffB);
;             PG8_BAR; PG8_WAIT_L(0); PG8_MMA(0, 1, At, B1); PG8_BAR;
;             PG8_LDA(At, 1, 1); PG8_STAGE(PG8_SA(1, 0), a3, voffA);
;             PG8_BAR; PG8_WAIT_L(0); PG8_MMA(1, 0, At, B0); PG8_BAR; PG8_SCHED;
;             PG8_STAGE(PG8_SB(1, 1), b3 + hstep, voffB);
;             PG8_WAIT_V(6); PG8_BAR; PG8_MMA(1, 1, At, B1); PG8_BAR;
;     __device__ __forceinline__ void operator()(const f32x4 (&acc)[2][2][4][2], const pg8::Unit& u, int wr, int wc, int fr, int fq) const {
;         const int row0 = u.pm * 256 + wr * 64 + fr; const int col0 = u.pn * 256 + wc * 32 + 8 * fq;
; #pragma unroll
;         for (int ai = 0; ai < 2; ++ai)
; #pragma unroll
;             for (int m = 0; m < 4; ++m) { const int row = row0 + ai * 128 + m * 16; bf16_t* rowp = O + (size_t)row * ldc + col0;
; #pragma unroll
;                 for (int bj = 0; bj < 2; ++bj) { f32x4 v0 = acc[ai][bj][m][0], v1 = acc[ai][bj][m][1];
;                     if (ACT == 1) {
; #pragma unroll
;                         for (int j = 0; j < 4; ++j) { float a = fmaxf(v0[j], 0.f), b = fmaxf(v1[j], 0.f); v0[j] = a * a; v1[j] = b * b; } }
;                     if (ACT == 0) { if (u.pn == (C_G / 256) && bj == 0 && wc == 0 && fq < 2) { float* gp = gate + (size_t)row * 16 + 8 * fq; *(f32x4*)gp = v0; *(f32x4*)(gp + 4) = v1; } }
	s_waitcnt lgkmcnt(0)
	v_mfma_f32_16x16x32_bf16 v[126:129], v[142:145], v[162:165], v[126:129]
	v_mfma_f32_16x16x32_bf16 v[122:125], v[154:157], v[162:165], v[122:125]
	v_mfma_f32_16x16x32_bf16 v[114:117], v[142:145], v[170:173], v[114:117]
	v_mfma_f32_16x16x32_bf16 v[106:109], v[154:157], v[170:173], v[106:109]
	v_mfma_f32_16x16x32_bf16 v[98:101], v[142:145], v[178:181], v[98:101]
	v_mfma_f32_16x16x32_bf16 v[90:93], v[154:157], v[178:181], v[90:93]
	v_mfma_f32_16x16x32_bf16 v[82:85], v[142:145], v[186:189], v[82:85]
	v_mfma_f32_16x16x32_bf16 v[74:77], v[154:157], v[186:189], v[74:77]
	v_mfma_f32_16x16x32_bf16 v[126:129], v[150:153], v[166:169], v[126:129]
	v_mfma_f32_16x16x32_bf16 v[122:125], v[158:161], v[166:169], v[122:125]
	v_mfma_f32_16x16x32_bf16 v[114:117], v[150:153], v[174:177], v[114:117]
	v_mfma_f32_16x16x32_bf16 v[106:109], v[158:161], v[174:177], v[106:109]
	v_mfma_f32_16x16x32_bf16 v[98:101], v[150:153], v[182:185], v[98:101]
	v_mfma_f32_16x16x32_bf16 v[90:93], v[158:161], v[182:185], v[90:93]
	v_mfma_f32_16x16x32_bf16 v[82:85], v[150:153], v[190:193], v[82:85]
	v_mfma_f32_16x16x32_bf16 v[74:77], v[158:161], v[190:193], v[74:77]
	s_barrier
	s_add_i32 s20, 0, 0x1c000
	s_add_i32 s21, s39, s23
	s_add_u32 s40, s18, 0x80
	s_addc_u32 s41, s19, 0
	s_mov_b32 m0, s21
	ds_read_b128 v[194:197], v221
	ds_read_b128 v[198:201], v221 offset:1024
	ds_read_b128 v[202:205], v221 offset:2048
	ds_read_b128 v[206:209], v221 offset:3072
	global_load_lds_dwordx4 v0, s[40:41]
	s_add_i32 m0, s21, 0x2000
	s_nop 0
	global_load_lds_dwordx4 v130, s[40:41]
	s_barrier
	s_waitcnt lgkmcnt(0)
	v_mfma_f32_16x16x32_bf16 v[118:121], v[194:197], v[162:165], v[118:121]
	v_mfma_f32_16x16x32_bf16 v[110:113], v[202:205], v[162:165], v[110:113]
	v_mfma_f32_16x16x32_bf16 v[102:105], v[194:197], v[170:173], v[102:105]
	v_mfma_f32_16x16x32_bf16 v[94:97], v[202:205], v[170:173], v[94:97]
	v_mfma_f32_16x16x32_bf16 v[86:89], v[194:197], v[178:181], v[86:89]
	v_mfma_f32_16x16x32_bf16 v[78:81], v[202:205], v[178:181], v[78:81]
	v_mfma_f32_16x16x32_bf16 v[70:73], v[194:197], v[186:189], v[70:73]
	v_mfma_f32_16x16x32_bf16 v[66:69], v[202:205], v[186:189], v[66:69]
	v_mfma_f32_16x16x32_bf16 v[118:121], v[198:201], v[166:169], v[118:121]
	v_mfma_f32_16x16x32_bf16 v[110:113], v[206:209], v[166:169], v[110:113]
	v_mfma_f32_16x16x32_bf16 v[102:105], v[198:201], v[174:177], v[102:105]
	v_mfma_f32_16x16x32_bf16 v[94:97], v[206:209], v[174:177], v[94:97]
	v_mfma_f32_16x16x32_bf16 v[86:89], v[198:201], v[182:185], v[86:89]
	v_mfma_f32_16x16x32_bf16 v[78:81], v[206:209], v[182:185], v[78:81]
	v_mfma_f32_16x16x32_bf16 v[70:73], v[198:201], v[190:193], v[70:73]
	v_mfma_f32_16x16x32_bf16 v[66:69], v[206:209], v[190:193], v[66:69]
	s_mov_b32 m0, s28
	s_barrier
	ds_read_b128 v[162:165], v149 offset:49152
	ds_read_b128 v[166:169], v149 offset:50176
	ds_read_b128 v[170:173], v149 offset:51200
	ds_read_b128 v[174:177], v149 offset:52224
	ds_read_b128 v[178:181], v149 offset:53248
	ds_read_b128 v[182:185], v149 offset:54272
	ds_read_b128 v[186:189], v149 offset:55296
	ds_read_b128 v[190:193], v149 offset:56320
	global_load_lds_dwordx4 v134, s[44:45]
	s_mov_b32 m0, s29
	s_nop 0
	global_load_lds_dwordx4 v132, s[44:45]
	s_barrier
	s_waitcnt lgkmcnt(0)
	v_mfma_f32_16x16x32_bf16 v[62:65], v[142:145], v[162:165], v[62:65]
	v_mfma_f32_16x16x32_bf16 v[58:61], v[154:157], v[162:165], v[58:61]
	v_mfma_f32_16x16x32_bf16 v[50:53], v[142:145], v[170:173], v[50:53]
	v_mfma_f32_16x16x32_bf16 v[42:45], v[154:157], v[170:173], v[42:45]
	v_mfma_f32_16x16x32_bf16 v[34:37], v[142:145], v[178:181], v[34:37]
	v_mfma_f32_16x16x32_bf16 v[26:29], v[154:157], v[178:181], v[26:29]
	v_mfma_f32_16x16x32_bf16 v[18:21], v[142:145], v[186:189], v[18:21]
	v_mfma_f32_16x16x32_bf16 v[10:13], v[154:157], v[186:189], v[10:13]
	v_mfma_f32_16x16x32_bf16 v[62:65], v[150:153], v[166:169], v[62:65]
	v_mfma_f32_16x16x32_bf16 v[58:61], v[158:161], v[166:169], v[58:61]
	v_mfma_f32_16x16x32_bf16 v[50:53], v[150:153], v[174:177], v[50:53]
	v_mfma_f32_16x16x32_bf16 v[42:45], v[158:161], v[174:177], v[42:45]
	v_mfma_f32_16x16x32_bf16 v[34:37], v[150:153], v[182:185], v[34:37]
	v_mfma_f32_16x16x32_bf16 v[26:29], v[158:161], v[182:185], v[26:29]
	v_mfma_f32_16x16x32_bf16 v[18:21], v[150:153], v[190:193], v[18:21]
	v_mfma_f32_16x16x32_bf16 v[10:13], v[158:161], v[190:193], v[10:13]
	s_barrier
	s_add_u32 s18, s18, 0x80080
	s_addc_u32 s19, s19, 0
	s_add_i32 s20, s20, s23
	s_mov_b32 m0, s20
	s_nop 0
	global_load_lds_dwordx4 v0, s[18:19]
	s_add_i32 m0, s20, 0x2000
	s_nop 0
	global_load_lds_dwordx4 v130, s[18:19]
	s_waitcnt vmcnt(6)
	s_barrier
	v_mfma_f32_16x16x32_bf16 v[54:57], v[194:197], v[162:165], v[54:57]
	v_mfma_f32_16x16x32_bf16 v[46:49], v[202:205], v[162:165], v[46:49]
	v_mfma_f32_16x16x32_bf16 v[38:41], v[194:197], v[170:173], v[38:41]
	v_mfma_f32_16x16x32_bf16 v[30:33], v[202:205], v[170:173], v[30:33]
	v_mfma_f32_16x16x32_bf16 v[22:25], v[194:197], v[178:181], v[22:25]
	v_mfma_f32_16x16x32_bf16 v[14:17], v[202:205], v[178:181], v[14:17]
	v_mfma_f32_16x16x32_bf16 v[6:9], v[194:197], v[186:189], v[6:9]
	v_mfma_f32_16x16x32_bf16 v[2:5], v[202:205], v[186:189], v[2:5]
	v_mfma_f32_16x16x32_bf16 v[54:57], v[198:201], v[166:169], v[54:57]
	v_mfma_f32_16x16x32_bf16 v[46:49], v[206:209], v[166:169], v[46:49]
	v_mfma_f32_16x16x32_bf16 v[38:41], v[198:201], v[174:177], v[38:41]
	v_mfma_f32_16x16x32_bf16 v[30:33], v[206:209], v[174:177], v[30:33]
	v_mfma_f32_16x16x32_bf16 v[22:25], v[198:201], v[182:185], v[22:25]
	v_mfma_f32_16x16x32_bf16 v[14:17], v[206:209], v[182:185], v[14:17]
	v_mfma_f32_16x16x32_bf16 v[6:9], v[198:201], v[190:193], v[6:9]
	v_mfma_f32_16x16x32_bf16 v[2:5], v[206:209], v[190:193], v[2:5]
	s_add_i32 s38, s38, 2
	s_add_u32 s16, s16, 0x100
	s_addc_u32 s17, s17, 0
	s_add_u32 s36, s36, 0x100
	s_addc_u32 s37, s37, 0
	s_cmp_gt_u32 s38, 29
	s_barrier
	s_cbranch_scc0 .LBB0_342
	s_cmp_eq_u32 s3, 18
	s_cselect_b64 s[16:17], -1, 0
	v_lshl_add_u32 v142, s31, 8, v146
	s_and_b64 s[16:17], s[6:7], s[16:17]
	v_ashrrev_i32_e32 v143, 31, v142
	s_and_b64 s[16:17], s[16:17], s[0:1]
	s_and_saveexec_b64 s[18:19], s[16:17]
	s_cbranch_execz .LBB0_345
	v_lshlrev_b64 v[144:145], 6, v[142:143]
	v_lshl_add_u64 v[144:145], v[136:137], 0, v[144:145]
	global_store_dwordx4 v[144:145], v[126:129], off
	global_store_dwordx4 v[144:145], v[122:125], off offset:16

; #define PG8_STAGE(bufoff, gbase, voff) do { _Pragma("unroll") for (int _i = 0; _i < 2; ++_i) \
;         __builtin_amdgcn_global_load_lds((const unsigned*)((const char*)(gbase) + (voff)[_i]), (LAS unsigned*)(lds + (bufoff) + ldsw + _i * 8192), 16, 0, 0); } while (0)
; #define PG8_LDA(dst, b, h) do { _Pragma("unroll") for (int m = 0; m < 4; ++m) _Pragma("unroll") for (int k = 0; k < 2; ++k) dst[m][k] = *(const LAS bf16x8*)(lds + PG8_SA(b, h) + aoff + m * 2048 + k * 1024); } while (0)
; template <class Epi, class Sched>
; __device__ __forceinline__ void gemm_phase(LAS unsigned char* lds, const Gemm g, const Sched& S, const Epi& E) {
;     ...
;     f32x4 acc[2][2][4][2];
; #pragma unroll
;     for (int a = 0; a < 2; ++a)
; #pragma unroll
;         for (int b = 0; b < 2; ++b)
; #pragma unroll
;             for (int m = 0; m < 4; ++m)
; #pragma unroll
;                 for (int n = 0; n < 2; ++n) acc[a][b][m][n] = (f32x4){0.f, 0.f, 0.f, 0.f};
;     bf16x8 At[4][2], B0[2][2], B1[2][2];
;     const char* cA = (const char*)g.A + (size_t)cur.pm * tstep; const char* cB = (const char*)g.Bt + (size_t)cur.pn * tstep;
;     S.a_ready(cur);
;     PG8_STAGE(PG8_SB(0, 0), cB, voffB); PG8_STAGE(PG8_SA(0, 0), cA, voffA); PG8_STAGE(PG8_SB(0, 1), cB + hstep, voffB); PG8_STAGE(PG8_SA(0, 1), cA + hstep, voffA);
;     if (wr == 1) PG8_BAR;
;     PG8_WAIT_V(4); PG8_BAR;
;     PG8_STAGE(PG8_SB(1, 0), cB + kstep, voffB); PG8_STAGE(PG8_SA(1, 0), cA + kstep, voffA); PG8_STAGE(PG8_SB(1, 1), cB + hstep + kstep, voffB);
;     PG8_WAIT_V(6); PG8_BAR;
;     for (;;) {
;         const bool has_next = S.next(ui + 1, nxt);
;         const char* nA = has_next ? (const char*)g.A + (size_t)nxt.pm * tstep : cA; const char* nB = has_next ? (const char*)g.Bt + (size_t)nxt.pn * tstep : cB;
;         for (int t = 0; t < nt; t += 2) {
;             const bool last = (t == nt - 2);
;             const char* a1 = cA + (size_t)(t + 1) * kstep;
;             const char* a2 = last ? nA : cA + (size_t)(t + 2) * kstep; const char* b2 = last ? nB : cB + (size_t)(t + 2) * kstep;
;             const char* a3 = a2 + kstep; const char* b3 = b2 + kstep;
;             if (last && has_next) S.a_ready(nxt);
;             PG8_LDB(B0, 0, 0); PG8_SCHED; PG8_LDA(At, 0, 0); PG8_STAGE(PG8_SA(1, 1), a1 + hstep, voffA);
;             PG8_WAIT_L(8); PG8_BAR; PG8_WAIT_L(0); PG8_MMA(0, 0, At, B0); PG8_BAR; PG8_SCHED;
.LBB0_1278:
	v_mov_b64_e32 v[2:3], s[4:5]
	s_ashr_i32 s11, s10, 31
	v_cmp_lt_i64_e32 vcc, s[12:13], v[2:3]
	s_lshl_b64 s[12:13], s[10:11], 20
	s_add_u32 s12, s56, s12
	s_addc_u32 s13, s57, s13
	s_and_b64 s[14:15], vcc, exec
	s_cselect_b32 s3, s13, s21
	s_cselect_b32 s11, s12, s20
	s_ashr_i32 s9, s8, 31
	s_lshl_b64 s[14:15], s[8:9], 20
	s_add_u32 s14, s28, s14
	s_addc_u32 s15, s29, s15
	s_and_b64 s[24:25], vcc, exec
	s_cselect_b32 s9, s15, s23
	s_cselect_b32 s40, s14, s22
	s_add_u32 s20, s20, 0x80080
	s_addc_u32 s21, s21, 0
	s_add_u32 s41, s22, 0x100
	v_mov_b32_e32 v2, 0
	s_addc_u32 s42, s23, 0
	s_mov_b32 s43, -2
	v_mov_b32_e32 v3, v2
	v_mov_b32_e32 v4, v2
	v_mov_b32_e32 v5, v2
	v_mov_b32_e32 v6, v2
	v_mov_b32_e32 v7, v2
	v_mov_b32_e32 v8, v2
	v_mov_b32_e32 v9, v2
	v_mov_b32_e32 v18, v2
	v_mov_b32_e32 v19, v2
	v_mov_b32_e32 v20, v2
	v_mov_b32_e32 v21, v2
	v_mov_b32_e32 v22, v2
	v_mov_b32_e32 v23, v2
	v_mov_b32_e32 v24, v2
	v_mov_b32_e32 v25, v2
	v_mov_b32_e32 v34, v2
	v_mov_b32_e32 v35, v2
	v_mov_b32_e32 v36, v2
	v_mov_b32_e32 v37, v2
	v_mov_b32_e32 v38, v2
	v_mov_b32_e32 v39, v2
	v_mov_b32_e32 v40, v2
	v_mov_b32_e32 v41, v2
	v_mov_b32_e32 v50, v2
	v_mov_b32_e32 v51, v2
	v_mov_b32_e32 v52, v2
	v_mov_b32_e32 v53, v2
	v_mov_b32_e32 v54, v2
	v_mov_b32_e32 v55, v2
	v_mov_b32_e32 v56, v2
	v_mov_b32_e32 v57, v2
	v_mov_b32_e32 v10, v2
	v_mov_b32_e32 v11, v2
	v_mov_b32_e32 v12, v2
	v_mov_b32_e32 v13, v2
	v_mov_b32_e32 v14, v2
	v_mov_b32_e32 v15, v2
	v_mov_b32_e32 v16, v2
	v_mov_b32_e32 v17, v2
	v_mov_b32_e32 v26, v2
	v_mov_b32_e32 v27, v2
	v_mov_b32_e32 v28, v2
	v_mov_b32_e32 v29, v2
	v_mov_b32_e32 v30, v2
	v_mov_b32_e32 v31, v2
	v_mov_b32_e32 v32, v2
	v_mov_b32_e32 v33, v2
	v_mov_b32_e32 v42, v2
	v_mov_b32_e32 v43, v2
	v_mov_b32_e32 v44, v2
	v_mov_b32_e32 v45, v2
	v_mov_b32_e32 v46, v2
	v_mov_b32_e32 v47, v2
	v_mov_b32_e32 v48, v2
	v_mov_b32_e32 v49, v2
	v_mov_b32_e32 v58, v2
	v_mov_b32_e32 v59, v2
	v_mov_b32_e32 v60, v2
	v_mov_b32_e32 v61, v2
	v_mov_b32_e32 v62, v2
	v_mov_b32_e32 v63, v2
	v_mov_b32_e32 v64, v2
	v_mov_b32_e32 v65, v2
	v_mov_b32_e32 v66, v2
	v_mov_b32_e32 v67, v2
	v_mov_b32_e32 v68, v2
	v_mov_b32_e32 v69, v2
	v_mov_b32_e32 v70, v2
	v_mov_b32_e32 v71, v2
	v_mov_b32_e32 v72, v2
	v_mov_b32_e32 v73, v2
	v_mov_b32_e32 v82, v2
	v_mov_b32_e32 v83, v2
	v_mov_b32_e32 v84, v2
	v_mov_b32_e32 v85, v2
	v_mov_b32_e32 v86, v2
	v_mov_b32_e32 v87, v2
	v_mov_b32_e32 v88, v2
	v_mov_b32_e32 v89, v2
	v_mov_b32_e32 v98, v2
	v_mov_b32_e32 v99, v2
	v_mov_b32_e32 v100, v2
	v_mov_b32_e32 v101, v2
	v_mov_b32_e32 v102, v2
	v_mov_b32_e32 v103, v2
	v_mov_b32_e32 v104, v2
	v_mov_b32_e32 v105, v2
	v_mov_b32_e32 v114, v2
	v_mov_b32_e32 v115, v2
	v_mov_b32_e32 v116, v2
	v_mov_b32_e32 v117, v2
	v_mov_b32_e32 v118, v2
	v_mov_b32_e32 v119, v2
	v_mov_b32_e32 v120, v2
	v_mov_b32_e32 v121, v2
	v_mov_b32_e32 v74, v2
	v_mov_b32_e32 v75, v2
	v_mov_b32_e32 v76, v2
	v_mov_b32_e32 v77, v2
	v_mov_b32_e32 v78, v2
	v_mov_b32_e32 v79, v2
	v_mov_b32_e32 v80, v2
	v_mov_b32_e32 v81, v2
	v_mov_b32_e32 v90, v2
	v_mov_b32_e32 v91, v2
	v_mov_b32_e32 v92, v2
	v_mov_b32_e32 v93, v2
	v_mov_b32_e32 v94, v2
	v_mov_b32_e32 v95, v2
	v_mov_b32_e32 v96, v2
	v_mov_b32_e32 v97, v2
	v_mov_b32_e32 v106, v2
	v_mov_b32_e32 v107, v2
	v_mov_b32_e32 v108, v2
	v_mov_b32_e32 v109, v2
	v_mov_b32_e32 v110, v2
	v_mov_b32_e32 v111, v2
	v_mov_b32_e32 v112, v2
	v_mov_b32_e32 v113, v2
	v_mov_b32_e32 v122, v2
	v_mov_b32_e32 v123, v2
	v_mov_b32_e32 v124, v2
	v_mov_b32_e32 v125, v2
	v_mov_b32_e32 v126, v2
	v_mov_b32_e32 v127, v2
	v_mov_b32_e32 v128, v2
	v_mov_b32_e32 v129, v2
	v_readlane_b32 s47, v253, 6
	s_mov_b64 s[48:49], 0x80
	v_add_u32_e32 v211, 0x14000, v143
	v_add_u32_e32 v220, 0x18000, v143
	v_add_u32_e32 v221, 0x1c000, v143
	v_add_u32_e32 v210, s47, v143
.LBB0_1279:
	s_nop 0
	ds_read_b128 v[146:149], v210
	ds_read_b128 v[150:153], v210 offset:1024
	ds_read_b128 v[154:157], v210 offset:2048
	ds_read_b128 v[158:161], v210 offset:3072
	s_add_u32 s22, s20, 0xfff80080
	s_addc_u32 s23, s21, -1
	s_cmp_eq_u32 s43, 28
	s_cselect_b32 s25, s3, s23
	s_cselect_b32 s24, s11, s22
	s_cselect_b32 s23, s9, s42
	s_cselect_b32 s22, s40, s41
	s_add_i32 m0, s17, 0xc000
	ds_read_b128 v[162:165], v145
	ds_read_b128 v[166:169], v145 offset:1024
	ds_read_b128 v[170:173], v145 offset:2048
	ds_read_b128 v[174:177], v145 offset:3072
	ds_read_b128 v[178:181], v145 offset:4096
	ds_read_b128 v[182:185], v145 offset:5120
	ds_read_b128 v[186:189], v145 offset:6144
	ds_read_b128 v[190:193], v145 offset:7168
	global_load_lds_dwordx4 v136, s[20:21]
	s_add_i32 m0, s17, 0xe000
	s_nop 0
	global_load_lds_dwordx4 v138, s[20:21]
	s_waitcnt lgkmcnt(8)
	s_barrier
	s_waitcnt lgkmcnt(0)
	v_mfma_f32_16x16x32_bf16 v[126:129], v[146:149], v[162:165], v[126:129]
	v_mfma_f32_16x16x32_bf16 v[122:125], v[154:157], v[162:165], v[122:125]
	v_mfma_f32_16x16x32_bf16 v[110:113], v[146:149], v[170:173], v[110:113]
	v_mfma_f32_16x16x32_bf16 v[106:109], v[154:157], v[170:173], v[106:109]
	v_mfma_f32_16x16x32_bf16 v[94:97], v[146:149], v[178:181], v[94:97]
	v_mfma_f32_16x16x32_bf16 v[90:93], v[154:157], v[178:181], v[90:93]
	v_mfma_f32_16x16x32_bf16 v[78:81], v[146:149], v[186:189], v[78:81]
	v_mfma_f32_16x16x32_bf16 v[74:77], v[154:157], v[186:189], v[74:77]
	v_mfma_f32_16x16x32_bf16 v[126:129], v[150:153], v[166:169], v[126:129]
	v_mfma_f32_16x16x32_bf16 v[122:125], v[158:161], v[166:169], v[122:125]
	v_mfma_f32_16x16x32_bf16 v[110:113], v[150:153], v[174:177], v[110:113]
	v_mfma_f32_16x16x32_bf16 v[106:109], v[158:161], v[174:177], v[106:109]
	v_mfma_f32_16x16x32_bf16 v[94:97], v[150:153], v[182:185], v[94:97]
	v_mfma_f32_16x16x32_bf16 v[90:93], v[158:161], v[182:185], v[90:93]
	v_mfma_f32_16x16x32_bf16 v[78:81], v[150:153], v[190:193], v[78:81]
	v_mfma_f32_16x16x32_bf16 v[74:77], v[158:161], v[190:193], v[74:77]
	s_barrier
; #define PG8_STAGE(bufoff, gbase, voff) do { _Pragma("unroll") for (int _i = 0; _i < 2; ++_i) \
;         __builtin_amdgcn_global_load_lds((const unsigned*)((const char*)(gbase) + (voff)[_i]), (LAS unsigned*)(lds + (bufoff) + ldsw + _i * 8192), 16, 0, 0); } while (0)
; #define PG8_LDA(dst, b, h) do { _Pragma("unroll") for (int m = 0; m < 4; ++m) _Pragma("unroll") for (int k = 0; k < 2; ++k) dst[m][k] = *(const LAS bf16x8*)(lds + PG8_SA(b, h) + aoff + m * 2048 + k * 1024); } while (0)
; #define PG8_LDB(dst, b, h) do { _Pragma("unroll") for (int n = 0; n < 2; ++n) _Pragma("unroll") for (int k = 0; k < 2; ++k) dst[n][k] = *(const LAS bf16x8*)(lds + PG8_SB(b, h) + boff + n * 2048 + k * 1024); } while (0)
; #define PG8_MMA(ai, bj, At, Bt) do { __builtin_amdgcn_s_setprio(1); _Pragma("unroll") for (int m = 0; m < 4; ++m) _Pragma("unroll") for (int n = 0; n < 2; ++n) _Pragma("unroll") for (int k = 0; k < 2; ++k) \
;         acc[ai][bj][m][n] = __builtin_amdgcn_mfma_f32_16x16x32_bf16(Bt[n][k], At[m][k], acc[ai][bj][m][n], 0, 0, 0); __builtin_amdgcn_s_setprio(0); } while (0)
; #define PG8_WAIT_V(n) asm volatile("s_waitcnt vmcnt(" #n ")" ::: "memory")
; #define PG8_WAIT_L(n) asm volatile("s_waitcnt lgkmcnt(" #n ")" ::: "memory")
; #define PG8_BAR __builtin_amdgcn_s_barrier()
; #define PG8_SCHED __builtin_amdgcn_sched_barrier(0)
; template <class Epi, class Sched>
; __device__ __forceinline__ void gemm_phase(LAS unsigned char* lds, const Gemm g, const Sched& S, const Epi& E) {
;     ...
;             PG8_WAIT_L(8); PG8_BAR; PG8_WAIT_L(0); PG8_MMA(0, 0, At, B0); PG8_BAR; PG8_SCHED;
;             PG8_LDB(B1, 0, 1); PG8_STAGE(PG8_SB(0, 0), b2, voffB);
;             PG8_BAR; PG8_WAIT_L(0); PG8_MMA(0, 1, At, B1); PG8_BAR;
;             PG8_LDA(At, 0, 1); PG8_STAGE(PG8_SA(0, 0), a2, voffA);
;             PG8_BAR; PG8_WAIT_L(0); PG8_MMA(1, 0, At, B0); PG8_BAR; PG8_SCHED;
;             PG8_STAGE(PG8_SB(0, 1), b2 + hstep, voffB);
;             PG8_WAIT_V(6); PG8_BAR; PG8_MMA(1, 1, At, B1); PG8_BAR;
;             PG8_LDB(B0, 1, 0); PG8_SCHED; PG8_LDA(At, 1, 0); PG8_STAGE(PG8_SA(0, 1), a2 + hstep, voffA);
;             PG8_WAIT_L(8); PG8_BAR; PG8_WAIT_L(0); PG8_MMA(0, 0, At, B0); PG8_BAR; PG8_SCHED;
	s_add_i32 s46, 0, 0x14000
	s_add_i32 s44, s47, s30
	ds_read_b128 v[194:197], v211
	ds_read_b128 v[198:201], v211 offset:1024
	ds_read_b128 v[202:205], v211 offset:2048
	ds_read_b128 v[206:209], v211 offset:3072
	s_mov_b32 m0, s44
	s_nop 0
	global_load_lds_dwordx4 v0, s[22:23]
	s_add_i32 m0, s44, 0x2000
	s_nop 0
	global_load_lds_dwordx4 v130, s[22:23]
	s_barrier
	s_waitcnt lgkmcnt(0)
	v_mfma_f32_16x16x32_bf16 v[118:121], v[194:197], v[162:165], v[118:121]
	v_mfma_f32_16x16x32_bf16 v[114:117], v[202:205], v[162:165], v[114:117]
	v_mfma_f32_16x16x32_bf16 v[102:105], v[194:197], v[170:173], v[102:105]
	v_mfma_f32_16x16x32_bf16 v[98:101], v[202:205], v[170:173], v[98:101]
	v_mfma_f32_16x16x32_bf16 v[86:89], v[194:197], v[178:181], v[86:89]
	v_mfma_f32_16x16x32_bf16 v[82:85], v[202:205], v[178:181], v[82:85]
	v_mfma_f32_16x16x32_bf16 v[70:73], v[194:197], v[186:189], v[70:73]
	v_mfma_f32_16x16x32_bf16 v[66:69], v[202:205], v[186:189], v[66:69]
	v_mfma_f32_16x16x32_bf16 v[118:121], v[198:201], v[166:169], v[118:121]
	v_mfma_f32_16x16x32_bf16 v[114:117], v[206:209], v[166:169], v[114:117]
	v_mfma_f32_16x16x32_bf16 v[102:105], v[198:201], v[174:177], v[102:105]
	v_mfma_f32_16x16x32_bf16 v[98:101], v[206:209], v[174:177], v[98:101]
	v_mfma_f32_16x16x32_bf16 v[86:89], v[198:201], v[182:185], v[86:89]
	v_mfma_f32_16x16x32_bf16 v[82:85], v[206:209], v[182:185], v[82:85]
	v_mfma_f32_16x16x32_bf16 v[70:73], v[198:201], v[190:193], v[70:73]
	v_mfma_f32_16x16x32_bf16 v[66:69], v[206:209], v[190:193], v[66:69]
	s_mov_b32 m0, s17
	s_add_u32 s48, s24, 0x80
	s_addc_u32 s49, s25, 0
	s_barrier
	ds_read_b128 v[162:165], v145 offset:16384
	ds_read_b128 v[166:169], v145 offset:17408
	ds_read_b128 v[170:173], v145 offset:18432
	ds_read_b128 v[174:177], v145 offset:19456
	ds_read_b128 v[178:181], v145 offset:20480
	ds_read_b128 v[182:185], v145 offset:21504
	ds_read_b128 v[186:189], v145 offset:22528
	ds_read_b128 v[190:193], v145 offset:23552
	global_load_lds_dwordx4 v134, s[24:25]
	s_mov_b32 m0, s19
	s_nop 0
	global_load_lds_dwordx4 v132, s[24:25]
	s_barrier
	s_waitcnt lgkmcnt(0)
	v_mfma_f32_16x16x32_bf16 v[62:65], v[146:149], v[162:165], v[62:65]
	v_mfma_f32_16x16x32_bf16 v[58:61], v[154:157], v[162:165], v[58:61]
	v_mfma_f32_16x16x32_bf16 v[46:49], v[146:149], v[170:173], v[46:49]
	v_mfma_f32_16x16x32_bf16 v[42:45], v[154:157], v[170:173], v[42:45]
	v_mfma_f32_16x16x32_bf16 v[30:33], v[146:149], v[178:181], v[30:33]
	v_mfma_f32_16x16x32_bf16 v[26:29], v[154:157], v[178:181], v[26:29]
	v_mfma_f32_16x16x32_bf16 v[14:17], v[146:149], v[186:189], v[14:17]
	v_mfma_f32_16x16x32_bf16 v[10:13], v[154:157], v[186:189], v[10:13]
	v_mfma_f32_16x16x32_bf16 v[62:65], v[150:153], v[166:169], v[62:65]
	v_mfma_f32_16x16x32_bf16 v[58:61], v[158:161], v[166:169], v[58:61]
	v_mfma_f32_16x16x32_bf16 v[46:49], v[150:153], v[174:177], v[46:49]
	v_mfma_f32_16x16x32_bf16 v[42:45], v[158:161], v[174:177], v[42:45]
	v_mfma_f32_16x16x32_bf16 v[30:33], v[150:153], v[182:185], v[30:33]
	v_mfma_f32_16x16x32_bf16 v[26:29], v[158:161], v[182:185], v[26:29]
	v_mfma_f32_16x16x32_bf16 v[14:17], v[150:153], v[190:193], v[14:17]
	v_mfma_f32_16x16x32_bf16 v[10:13], v[158:161], v[190:193], v[10:13]
	s_barrier
	s_add_u32 s44, s22, 0x80000
	s_addc_u32 s45, s23, 0
	s_add_i32 s46, s46, s30
	s_mov_b32 m0, s46
	s_nop 0
	global_load_lds_dwordx4 v0, s[44:45]
	s_add_i32 m0, s46, 0x2000
	s_nop 0
	global_load_lds_dwordx4 v130, s[44:45]
	s_waitcnt vmcnt(6)
	s_barrier
	v_mfma_f32_16x16x32_bf16 v[54:57], v[194:197], v[162:165], v[54:57]
	v_mfma_f32_16x16x32_bf16 v[50:53], v[202:205], v[162:165], v[50:53]
	v_mfma_f32_16x16x32_bf16 v[38:41], v[194:197], v[170:173], v[38:41]
	v_mfma_f32_16x16x32_bf16 v[34:37], v[202:205], v[170:173], v[34:37]
	v_mfma_f32_16x16x32_bf16 v[22:25], v[194:197], v[178:181], v[22:25]
	v_mfma_f32_16x16x32_bf16 v[18:21], v[202:205], v[178:181], v[18:21]
	v_mfma_f32_16x16x32_bf16 v[6:9], v[194:197], v[186:189], v[6:9]
	v_mfma_f32_16x16x32_bf16 v[2:5], v[202:205], v[186:189], v[2:5]
	v_mfma_f32_16x16x32_bf16 v[54:57], v[198:201], v[166:169], v[54:57]
	v_mfma_f32_16x16x32_bf16 v[50:53], v[206:209], v[166:169], v[50:53]
	v_mfma_f32_16x16x32_bf16 v[38:41], v[198:201], v[174:177], v[38:41]
	v_mfma_f32_16x16x32_bf16 v[34:37], v[206:209], v[174:177], v[34:37]
	v_mfma_f32_16x16x32_bf16 v[22:25], v[198:201], v[182:185], v[22:25]
	v_mfma_f32_16x16x32_bf16 v[18:21], v[206:209], v[182:185], v[18:21]
	v_mfma_f32_16x16x32_bf16 v[6:9], v[198:201], v[190:193], v[6:9]
	v_mfma_f32_16x16x32_bf16 v[2:5], v[206:209], v[190:193], v[2:5]
	s_add_i32 s44, 0, 0x18000
	s_barrier
	ds_read_b128 v[146:149], v220
	ds_read_b128 v[150:153], v220 offset:1024
	ds_read_b128 v[154:157], v220 offset:2048
	ds_read_b128 v[158:161], v220 offset:3072
	s_add_u32 s24, s24, 0x80000
	s_addc_u32 s25, s25, 0
	s_mov_b32 m0, s35
	ds_read_b128 v[162:165], v145 offset:32768
	ds_read_b128 v[166:169], v145 offset:33792
	ds_read_b128 v[170:173], v145 offset:34816
	ds_read_b128 v[174:177], v145 offset:35840
	ds_read_b128 v[178:181], v145 offset:36864
	ds_read_b128 v[182:185], v145 offset:37888
	ds_read_b128 v[186:189], v145 offset:38912
	ds_read_b128 v[190:193], v145 offset:39936
	global_load_lds_dwordx4 v134, s[24:25]
	s_mov_b32 m0, s36
	s_nop 0
	global_load_lds_dwordx4 v132, s[24:25]
	s_waitcnt lgkmcnt(8)
	s_barrier
; #define PG8_STAGE(bufoff, gbase, voff) do { _Pragma("unroll") for (int _i = 0; _i < 2; ++_i) \
;         __builtin_amdgcn_global_load_lds((const unsigned*)((const char*)(gbase) + (voff)[_i]), (LAS unsigned*)(lds + (bufoff) + ldsw + _i * 8192), 16, 0, 0); } while (0)
; #define PG8_LDA(dst, b, h) do { _Pragma("unroll") for (int m = 0; m < 4; ++m) _Pragma("unroll") for (int k = 0; k < 2; ++k) dst[m][k] = *(const LAS bf16x8*)(lds + PG8_SA(b, h) + aoff + m * 2048 + k * 1024); } while (0)
; #define PG8_LDB(dst, b, h) do { _Pragma("unroll") for (int n = 0; n < 2; ++n) _Pragma("unroll") for (int k = 0; k < 2; ++k) dst[n][k] = *(const LAS bf16x8*)(lds + PG8_SB(b, h) + boff + n * 2048 + k * 1024); } while (0)
; #define PG8_MMA(ai, bj, At, Bt) do { __builtin_amdgcn_s_setprio(1); _Pragma("unroll") for (int m = 0; m < 4; ++m) _Pragma("unroll") for (int n = 0; n < 2; ++n) _Pragma("unroll") for (int k = 0; k < 2; ++k) \
;         acc[ai][bj][m][n] = __builtin_amdgcn_mfma_f32_16x16x32_bf16(Bt[n][k], At[m][k], acc[ai][bj][m][n], 0, 0, 0); __builtin_amdgcn_s_setprio(0); } while (0)
; #define PG8_WAIT_V(n) asm volatile("s_waitcnt vmcnt(" #n ")" ::: "memory")
; #define PG8_WAIT_L(n) asm volatile("s_waitcnt lgkmcnt(" #n ")" ::: "memory")
; #define PG8_BAR __builtin_amdgcn_s_barrier()
; #define PG8_SCHED __builtin_amdgcn_sched_barrier(0)
; template <class Epi, class Sched>
; __device__ __forceinline__ void gemm_phase(LAS unsigned char* lds, const Gemm g, const Sched& S, const Epi& E) {
;     ...
;             PG8_WAIT_L(8); PG8_BAR; PG8_WAIT_L(0); PG8_MMA(0, 0, At, B0); PG8_BAR; PG8_SCHED;
;             PG8_LDB(B1, 1, 1); PG8_STAGE(PG8_SB(1, 0), b3, voffB);
;             PG8_BAR; PG8_WAIT_L(0); PG8_MMA(0, 1, At, B1); PG8_BAR;
;             PG8_LDA(At, 1, 1); PG8_STAGE(PG8_SA(1, 0), a3, voffA);
;             PG8_BAR; PG8_WAIT_L(0); PG8_MMA(1, 0, At, B0); PG8_BAR; PG8_SCHED;
;             PG8_STAGE(PG8_SB(1, 1), b3 + hstep, voffB);
;             PG8_WAIT_V(6); PG8_BAR; PG8_MMA(1, 1, At, B1); PG8_BAR;
	s_waitcnt lgkmcnt(0)
	v_mfma_f32_16x16x32_bf16 v[126:129], v[146:149], v[162:165], v[126:129]
	v_mfma_f32_16x16x32_bf16 v[122:125], v[154:157], v[162:165], v[122:125]
	v_mfma_f32_16x16x32_bf16 v[110:113], v[146:149], v[170:173], v[110:113]
	v_mfma_f32_16x16x32_bf16 v[106:109], v[154:157], v[170:173], v[106:109]
	v_mfma_f32_16x16x32_bf16 v[94:97], v[146:149], v[178:181], v[94:97]
	v_mfma_f32_16x16x32_bf16 v[90:93], v[154:157], v[178:181], v[90:93]
	v_mfma_f32_16x16x32_bf16 v[78:81], v[146:149], v[186:189], v[78:81]
	v_mfma_f32_16x16x32_bf16 v[74:77], v[154:157], v[186:189], v[74:77]
	v_mfma_f32_16x16x32_bf16 v[126:129], v[150:153], v[166:169], v[126:129]
	v_mfma_f32_16x16x32_bf16 v[122:125], v[158:161], v[166:169], v[122:125]
	v_mfma_f32_16x16x32_bf16 v[110:113], v[150:153], v[174:177], v[110:113]
	v_mfma_f32_16x16x32_bf16 v[106:109], v[158:161], v[174:177], v[106:109]
	v_mfma_f32_16x16x32_bf16 v[94:97], v[150:153], v[182:185], v[94:97]
	v_mfma_f32_16x16x32_bf16 v[90:93], v[158:161], v[182:185], v[90:93]
	v_mfma_f32_16x16x32_bf16 v[78:81], v[150:153], v[190:193], v[78:81]
	v_mfma_f32_16x16x32_bf16 v[74:77], v[158:161], v[190:193], v[74:77]
	s_barrier
	s_add_i32 s24, 0, 0x1c000
	s_add_i32 s25, s44, s30
	s_add_u32 s44, s22, 0x80
	s_addc_u32 s45, s23, 0
	s_mov_b32 m0, s25
	ds_read_b128 v[194:197], v221
	ds_read_b128 v[198:201], v221 offset:1024
	ds_read_b128 v[202:205], v221 offset:2048
	ds_read_b128 v[206:209], v221 offset:3072
	global_load_lds_dwordx4 v0, s[44:45]
	s_add_i32 m0, s25, 0x2000
	s_nop 0
	global_load_lds_dwordx4 v130, s[44:45]
	s_barrier
	s_waitcnt lgkmcnt(0)
	v_mfma_f32_16x16x32_bf16 v[118:121], v[194:197], v[162:165], v[118:121]
	v_mfma_f32_16x16x32_bf16 v[114:117], v[202:205], v[162:165], v[114:117]
	v_mfma_f32_16x16x32_bf16 v[102:105], v[194:197], v[170:173], v[102:105]
	v_mfma_f32_16x16x32_bf16 v[98:101], v[202:205], v[170:173], v[98:101]
	v_mfma_f32_16x16x32_bf16 v[86:89], v[194:197], v[178:181], v[86:89]
	v_mfma_f32_16x16x32_bf16 v[82:85], v[202:205], v[178:181], v[82:85]
	v_mfma_f32_16x16x32_bf16 v[70:73], v[194:197], v[186:189], v[70:73]
	v_mfma_f32_16x16x32_bf16 v[66:69], v[202:205], v[186:189], v[66:69]
	v_mfma_f32_16x16x32_bf16 v[118:121], v[198:201], v[166:169], v[118:121]
	v_mfma_f32_16x16x32_bf16 v[114:117], v[206:209], v[166:169], v[114:117]
	v_mfma_f32_16x16x32_bf16 v[102:105], v[198:201], v[174:177], v[102:105]
	v_mfma_f32_16x16x32_bf16 v[98:101], v[206:209], v[174:177], v[98:101]
	v_mfma_f32_16x16x32_bf16 v[86:89], v[198:201], v[182:185], v[86:89]
	v_mfma_f32_16x16x32_bf16 v[82:85], v[206:209], v[182:185], v[82:85]
	v_mfma_f32_16x16x32_bf16 v[70:73], v[198:201], v[190:193], v[70:73]
	v_mfma_f32_16x16x32_bf16 v[66:69], v[206:209], v[190:193], v[66:69]
	s_mov_b32 m0, s37
	s_barrier
	ds_read_b128 v[162:165], v145 offset:49152
	ds_read_b128 v[166:169], v145 offset:50176
	ds_read_b128 v[170:173], v145 offset:51200
	ds_read_b128 v[174:177], v145 offset:52224
	ds_read_b128 v[178:181], v145 offset:53248
	ds_read_b128 v[182:185], v145 offset:54272
	ds_read_b128 v[186:189], v145 offset:55296
	ds_read_b128 v[190:193], v145 offset:56320
	global_load_lds_dwordx4 v134, s[48:49]
	s_mov_b32 m0, s38
	s_nop 0
	global_load_lds_dwordx4 v132, s[48:49]
	s_barrier
	s_waitcnt lgkmcnt(0)
	v_mfma_f32_16x16x32_bf16 v[62:65], v[146:149], v[162:165], v[62:65]
	v_mfma_f32_16x16x32_bf16 v[58:61], v[154:157], v[162:165], v[58:61]
	v_mfma_f32_16x16x32_bf16 v[46:49], v[146:149], v[170:173], v[46:49]
	v_mfma_f32_16x16x32_bf16 v[42:45], v[154:157], v[170:173], v[42:45]
	v_mfma_f32_16x16x32_bf16 v[30:33], v[146:149], v[178:181], v[30:33]
	v_mfma_f32_16x16x32_bf16 v[26:29], v[154:157], v[178:181], v[26:29]
	v_mfma_f32_16x16x32_bf16 v[14:17], v[146:149], v[186:189], v[14:17]
	v_mfma_f32_16x16x32_bf16 v[10:13], v[154:157], v[186:189], v[10:13]
	v_mfma_f32_16x16x32_bf16 v[62:65], v[150:153], v[166:169], v[62:65]
	v_mfma_f32_16x16x32_bf16 v[58:61], v[158:161], v[166:169], v[58:61]
	v_mfma_f32_16x16x32_bf16 v[46:49], v[150:153], v[174:177], v[46:49]
	v_mfma_f32_16x16x32_bf16 v[42:45], v[158:161], v[174:177], v[42:45]
	v_mfma_f32_16x16x32_bf16 v[30:33], v[150:153], v[182:185], v[30:33]
	v_mfma_f32_16x16x32_bf16 v[26:29], v[158:161], v[182:185], v[26:29]
	v_mfma_f32_16x16x32_bf16 v[14:17], v[150:153], v[190:193], v[14:17]
	v_mfma_f32_16x16x32_bf16 v[10:13], v[158:161], v[190:193], v[10:13]
	s_barrier
	s_add_u32 s22, s22, 0x80080
	s_addc_u32 s23, s23, 0
	s_add_i32 s24, s24, s30
	s_mov_b32 m0, s24
	s_nop 0
	global_load_lds_dwordx4 v0, s[22:23]
	s_add_i32 m0, s24, 0x2000
	s_nop 0
	global_load_lds_dwordx4 v130, s[22:23]
	s_waitcnt vmcnt(6)
	s_barrier
	v_mfma_f32_16x16x32_bf16 v[54:57], v[194:197], v[162:165], v[54:57]
	v_mfma_f32_16x16x32_bf16 v[50:53], v[202:205], v[162:165], v[50:53]
	v_mfma_f32_16x16x32_bf16 v[38:41], v[194:197], v[170:173], v[38:41]
	v_mfma_f32_16x16x32_bf16 v[34:37], v[202:205], v[170:173], v[34:37]
	v_mfma_f32_16x16x32_bf16 v[22:25], v[194:197], v[178:181], v[22:25]
	v_mfma_f32_16x16x32_bf16 v[18:21], v[202:205], v[178:181], v[18:21]
	v_mfma_f32_16x16x32_bf16 v[6:9], v[194:197], v[186:189], v[6:9]
	v_mfma_f32_16x16x32_bf16 v[2:5], v[202:205], v[186:189], v[2:5]
	v_mfma_f32_16x16x32_bf16 v[54:57], v[198:201], v[166:169], v[54:57]
	v_mfma_f32_16x16x32_bf16 v[50:53], v[206:209], v[166:169], v[50:53]
	v_mfma_f32_16x16x32_bf16 v[38:41], v[198:201], v[174:177], v[38:41]
	v_mfma_f32_16x16x32_bf16 v[34:37], v[206:209], v[174:177], v[34:37]
	v_mfma_f32_16x16x32_bf16 v[22:25], v[198:201], v[182:185], v[22:25]
	v_mfma_f32_16x16x32_bf16 v[18:21], v[206:209], v[182:185], v[18:21]
	v_mfma_f32_16x16x32_bf16 v[6:9], v[198:201], v[190:193], v[6:9]
	v_mfma_f32_16x16x32_bf16 v[2:5], v[206:209], v[190:193], v[2:5]
	s_add_i32 s43, s43, 2
	s_add_u32 s20, s20, 0x100
	s_addc_u32 s21, s21, 0
	s_add_u32 s41, s41, 0x100
	s_addc_u32 s42, s42, 0
	s_cmp_gt_u32 s43, 29
	s_barrier
; __device__ __forceinline__ unsigned cvt_pk_bf16(float lo, float hi) { f32x2_t v = {lo, hi}; bf16x2_t b = __builtin_convertvector(v, bf16x2_t); return __builtin_bit_cast(unsigned, b); }
;     __device__ __forceinline__ void operator()(const f32x4 (&acc)[2][2][4][2], const pg8::Unit& u, int wr, int wc, int fr, int fq) const {
;         const int row0 = u.pm * 256 + wr * 64 + fr; const int col0 = u.pn * 256 + wc * 32 + 8 * fq;
; #pragma unroll
;         for (int ai = 0; ai < 2; ++ai)
; #pragma unroll
;             for (int m = 0; m < 4; ++m) { const int row = row0 + ai * 128 + m * 16; bf16_t* rowp = O + (size_t)row * ldc + col0;
; #pragma unroll
;                 for (int bj = 0; bj < 2; ++bj) { f32x4 v0 = acc[ai][bj][m][0], v1 = acc[ai][bj][m][1];
;                     if (ACT == 1) {
; #pragma unroll
;                         for (int j = 0; j < 4; ++j) { float a = fmaxf(v0[j], 0.f), b = fmaxf(v1[j], 0.f); v0[j] = a * a; v1[j] = b * b; } }
;                     if (ACT == 0) { if (u.pn == (C_G / 256) && bj == 0 && wc == 0 && fq < 2) { float* gp = gate + (size_t)row * 16 + 8 * fq; *(f32x4*)gp = v0; *(f32x4*)(gp + 4) = v1; } }
;                     u32x4 w; w.x = cvt_pk_bf16(v0[0], v0[1]); w.y = cvt_pk_bf16(v0[2], v0[3]); w.z = cvt_pk_bf16(v1[0], v1[1]); w.w = cvt_pk_bf16(v1[2], v1[3]);
;                     *(u32x4*)(rowp + bj * 128) = w; } }
	s_cbranch_scc0 .LBB0_1279
	v_lshl_add_u32 v146, s18, 8, v142
	v_lshl_or_b32 v140, s16, 8, v144
	v_ashrrev_i32_e32 v147, 31, v146
	v_ashrrev_i32_e32 v141, 31, v140
	v_lshlrev_b64 v[148:149], 14, v[146:147]
	v_max_f32_e32 v122, v122, v122
	v_max_f32_e32 v123, v123, v123
	v_lshl_add_u64 v[148:149], s[58:59], 0, v[148:149]
	v_lshlrev_b64 v[150:151], 1, v[140:141]
	v_max_f32_e32 v122, 0, v122
	v_max_f32_e32 v123, 0, v123
	v_lshl_add_u64 v[140:141], v[148:149], 0, v[150:151]
	v_pk_mul_f32 v[148:149], v[122:123], v[122:123]
	v_max_f32_e32 v123, v124, v124
	v_max_f32_e32 v126, v126, v126
	v_max_f32_e32 v127, v127, v127
	v_max_f32_e32 v122, v128, v128
	v_max_f32_e32 v124, 0, v123
	v_max_f32_e32 v123, v129, v129
	v_max_f32_e32 v125, v125, v125
	v_max_f32_e32 v126, 0, v126
	v_max_f32_e32 v127, 0, v127
	v_max_f32_e32 v122, 0, v122
	v_max_f32_e32 v123, 0, v123
	v_max_f32_e32 v125, 0, v125
	v_pk_mul_f32 v[126:127], v[126:127], v[126:127]
	v_pk_mul_f32 v[128:129], v[122:123], v[122:123]
	v_pk_mul_f32 v[152:153], v[124:125], v[124:125]
	v_max_f32_e32 v114, v114, v114
	v_max_f32_e32 v115, v115, v115
	v_cvt_pk_bf16_f32 v122, v126, v127
	v_cvt_pk_bf16_f32 v123, v128, v129
	v_cvt_pk_bf16_f32 v124, v148, v149
	v_cvt_pk_bf16_f32 v125, v152, v153
	v_max_f32_e32 v114, 0, v114
	v_max_f32_e32 v115, 0, v115
	global_store_dwordx4 v[140:141], v[122:125], off
	v_max_f32_e32 v118, v118, v118
	v_max_f32_e32 v119, v119, v119
	v_pk_mul_f32 v[122:123], v[114:115], v[114:115]
	v_max_f32_e32 v115, v116, v116
	v_max_f32_e32 v114, v120, v120
	v_max_f32_e32 v116, 0, v115
	v_max_f32_e32 v115, v121, v121
	v_max_f32_e32 v117, v117, v117
	v_max_f32_e32 v118, 0, v118
	v_max_f32_e32 v119, 0, v119
	v_max_f32_e32 v114, 0, v114
	v_max_f32_e32 v115, 0, v115
	v_max_f32_e32 v117, 0, v117
	v_pk_mul_f32 v[118:119], v[118:119], v[118:119]
	v_pk_mul_f32 v[120:121], v[114:115], v[114:115]
	v_pk_mul_f32 v[124:125], v[116:117], v[116:117]
	v_max_f32_e32 v106, v106, v106
	v_max_f32_e32 v107, v107, v107
	v_cvt_pk_bf16_f32 v114, v118, v119
	v_cvt_pk_bf16_f32 v115, v120, v121
	v_cvt_pk_bf16_f32 v116, v122, v123
	v_cvt_pk_bf16_f32 v117, v124, v125
	v_max_f32_e32 v106, 0, v106
	v_max_f32_e32 v107, 0, v107
	global_store_dwordx4 v[140:141], v[114:117], off offset:256
	v_max_f32_e32 v110, v110, v110
	v_max_f32_e32 v111, v111, v111
	v_or_b32_e32 v114, 16, v146
	v_pk_mul_f32 v[116:117], v[106:107], v[106:107]
	v_max_f32_e32 v107, v108, v108
	v_ashrrev_i32_e32 v115, 31, v114
	v_max_f32_e32 v106, v112, v112
	v_max_f32_e32 v108, 0, v107
	v_max_f32_e32 v107, v113, v113
	v_max_f32_e32 v109, v109, v109
	v_lshlrev_b64 v[114:115], 14, v[114:115]
	v_max_f32_e32 v110, 0, v110
	v_max_f32_e32 v111, 0, v111
	v_max_f32_e32 v106, 0, v106
	v_max_f32_e32 v107, 0, v107
	v_max_f32_e32 v109, 0, v109
	v_lshl_add_u64 v[114:115], s[58:59], 0, v[114:115]
	v_pk_mul_f32 v[110:111], v[110:111], v[110:111]
	v_pk_mul_f32 v[112:113], v[106:107], v[106:107]
	v_pk_mul_f32 v[118:119], v[108:109], v[108:109]
	v_max_f32_e32 v98, v98, v98
	v_max_f32_e32 v99, v99, v99
	v_lshl_add_u64 v[114:115], v[114:115], 0, v[150:151]
	v_cvt_pk_bf16_f32 v106, v110, v111
	v_cvt_pk_bf16_f32 v107, v112, v113
	v_cvt_pk_bf16_f32 v108, v116, v117
	v_cvt_pk_bf16_f32 v109, v118, v119
	v_max_f32_e32 v98, 0, v98
	v_max_f32_e32 v99, 0, v99
	global_store_dwordx4 v[114:115], v[106:109], off
	v_max_f32_e32 v102, v102, v102
	v_max_f32_e32 v103, v103, v103
	v_pk_mul_f32 v[106:107], v[98:99], v[98:99]
	v_max_f32_e32 v99, v100, v100
	v_max_f32_e32 v98, v104, v104
	v_max_f32_e32 v100, 0, v99
	v_max_f32_e32 v99, v105, v105
	v_max_f32_e32 v101, v101, v101
	v_max_f32_e32 v102, 0, v102
	v_max_f32_e32 v103, 0, v103
	v_max_f32_e32 v98, 0, v98
	v_max_f32_e32 v99, 0, v99
	v_max_f32_e32 v101, 0, v101
	v_pk_mul_f32 v[102:103], v[102:103], v[102:103]
	v_pk_mul_f32 v[104:105], v[98:99], v[98:99]
	v_pk_mul_f32 v[108:109], v[100:101], v[100:101]
	v_max_f32_e32 v90, v90, v90
	v_max_f32_e32 v91, v91, v91
	v_cvt_pk_bf16_f32 v98, v102, v103
	v_cvt_pk_bf16_f32 v99, v104, v105
	v_cvt_pk_bf16_f32 v100, v106, v107
	v_cvt_pk_bf16_f32 v101, v108, v109
	v_max_f32_e32 v90, 0, v90
	v_max_f32_e32 v91, 0, v91
	global_store_dwordx4 v[114:115], v[98:101], off offset:256
	v_max_f32_e32 v94, v94, v94
	v_max_f32_e32 v95, v95, v95
	v_or_b32_e32 v98, 32, v146
	v_pk_mul_f32 v[100:101], v[90:91], v[90:91]
	v_max_f32_e32 v91, v92, v92
	v_ashrrev_i32_e32 v99, 31, v98
	v_max_f32_e32 v90, v96, v96
	v_max_f32_e32 v92, 0, v91
	v_max_f32_e32 v91, v97, v97
	v_max_f32_e32 v93, v93, v93
	v_lshlrev_b64 v[98:99], 14, v[98:99]
	v_max_f32_e32 v94, 0, v94
	v_max_f32_e32 v95, 0, v95
	v_max_f32_e32 v90, 0, v90
	v_max_f32_e32 v91, 0, v91
	v_max_f32_e32 v93, 0, v93
	v_lshl_add_u64 v[98:99], s[58:59], 0, v[98:99]
	v_pk_mul_f32 v[94:95], v[94:95], v[94:95]
	v_pk_mul_f32 v[96:97], v[90:91], v[90:91]
	v_pk_mul_f32 v[102:103], v[92:93], v[92:93]
	v_max_f32_e32 v82, v82, v82
	v_max_f32_e32 v83, v83, v83
	v_lshl_add_u64 v[98:99], v[98:99], 0, v[150:151]
	v_cvt_pk_bf16_f32 v90, v94, v95
	v_cvt_pk_bf16_f32 v91, v96, v97
	v_cvt_pk_bf16_f32 v92, v100, v101
	v_cvt_pk_bf16_f32 v93, v102, v103
	v_max_f32_e32 v82, 0, v82
	v_max_f32_e32 v83, 0, v83
	global_store_dwordx4 v[98:99], v[90:93], off
	v_max_f32_e32 v86, v86, v86
	v_max_f32_e32 v87, v87, v87
	v_pk_mul_f32 v[90:91], v[82:83], v[82:83]
	v_max_f32_e32 v83, v84, v84
	v_max_f32_e32 v82, v88, v88
	v_max_f32_e32 v84, 0, v83
	v_max_f32_e32 v83, v89, v89
	v_max_f32_e32 v85, v85, v85
	v_max_f32_e32 v86, 0, v86
	v_max_f32_e32 v87, 0, v87
	v_max_f32_e32 v82, 0, v82
	v_max_f32_e32 v83, 0, v83
	v_max_f32_e32 v85, 0, v85
	v_pk_mul_f32 v[86:87], v[86:87], v[86:87]
	v_pk_mul_f32 v[88:89], v[82:83], v[82:83]
; __device__ __forceinline__ unsigned cvt_pk_bf16(float lo, float hi) { f32x2_t v = {lo, hi}; bf16x2_t b = __builtin_convertvector(v, bf16x2_t); return __builtin_bit_cast(unsigned, b); }
;     __device__ __forceinline__ void operator()(const f32x4 (&acc)[2][2][4][2], const pg8::Unit& u, int wr, int wc, int fr, int fq) const {
;     ...
;             for (int m = 0; m < 4; ++m) { const int row = row0 + ai * 128 + m * 16; bf16_t* rowp = O + (size_t)row * ldc + col0;
; #pragma unroll
;                 for (int bj = 0; bj < 2; ++bj) { f32x4 v0 = acc[ai][bj][m][0], v1 = acc[ai][bj][m][1];
;                     if (ACT == 1) {
; #pragma unroll
;                         for (int j = 0; j < 4; ++j) { float a = fmaxf(v0[j], 0.f), b = fmaxf(v1[j], 0.f); v0[j] = a * a; v1[j] = b * b; } }
;                     if (ACT == 0) { if (u.pn == (C_G / 256) && bj == 0 && wc == 0 && fq < 2) { float* gp = gate + (size_t)row * 16 + 8 * fq; *(f32x4*)gp = v0; *(f32x4*)(gp + 4) = v1; } }
;                     u32x4 w; w.x = cvt_pk_bf16(v0[0], v0[1]); w.y = cvt_pk_bf16(v0[2], v0[3]); w.z = cvt_pk_bf16(v1[0], v1[1]); w.w = cvt_pk_bf16(v1[2], v1[3]);
;                     *(u32x4*)(rowp + bj * 128) = w; } }
	v_pk_mul_f32 v[92:93], v[84:85], v[84:85]
	v_max_f32_e32 v74, v74, v74
	v_max_f32_e32 v75, v75, v75
	v_cvt_pk_bf16_f32 v82, v86, v87
	v_cvt_pk_bf16_f32 v83, v88, v89
	v_cvt_pk_bf16_f32 v84, v90, v91
	v_cvt_pk_bf16_f32 v85, v92, v93
	v_max_f32_e32 v74, 0, v74
	v_max_f32_e32 v75, 0, v75
	global_store_dwordx4 v[98:99], v[82:85], off offset:256
	v_max_f32_e32 v78, v78, v78
	v_max_f32_e32 v79, v79, v79
	v_or_b32_e32 v82, 48, v146
	v_pk_mul_f32 v[84:85], v[74:75], v[74:75]
	v_max_f32_e32 v75, v76, v76
	v_ashrrev_i32_e32 v83, 31, v82
	v_max_f32_e32 v74, v80, v80
	v_max_f32_e32 v76, 0, v75
	v_max_f32_e32 v75, v81, v81
	v_max_f32_e32 v77, v77, v77
	v_lshlrev_b64 v[82:83], 14, v[82:83]
	v_max_f32_e32 v78, 0, v78
	v_max_f32_e32 v79, 0, v79
	v_max_f32_e32 v74, 0, v74
	v_max_f32_e32 v75, 0, v75
	v_max_f32_e32 v77, 0, v77
	v_lshl_add_u64 v[82:83], s[58:59], 0, v[82:83]
	v_pk_mul_f32 v[78:79], v[78:79], v[78:79]
	v_pk_mul_f32 v[80:81], v[74:75], v[74:75]
	v_pk_mul_f32 v[86:87], v[76:77], v[76:77]
	v_max_f32_e32 v66, v66, v66
	v_max_f32_e32 v67, v67, v67
	v_lshl_add_u64 v[82:83], v[82:83], 0, v[150:151]
	v_cvt_pk_bf16_f32 v74, v78, v79
	v_cvt_pk_bf16_f32 v75, v80, v81
	v_cvt_pk_bf16_f32 v76, v84, v85
	v_cvt_pk_bf16_f32 v77, v86, v87
	v_max_f32_e32 v66, 0, v66
	v_max_f32_e32 v67, 0, v67
	global_store_dwordx4 v[82:83], v[74:77], off
	v_max_f32_e32 v70, v70, v70
	v_max_f32_e32 v71, v71, v71
	v_pk_mul_f32 v[74:75], v[66:67], v[66:67]
	v_max_f32_e32 v67, v68, v68
	v_max_f32_e32 v66, v72, v72
	v_max_f32_e32 v68, 0, v67
	v_max_f32_e32 v67, v73, v73
	v_max_f32_e32 v69, v69, v69
	v_max_f32_e32 v70, 0, v70
	v_max_f32_e32 v71, 0, v71
	v_max_f32_e32 v66, 0, v66
	v_max_f32_e32 v67, 0, v67
	v_max_f32_e32 v69, 0, v69
	v_pk_mul_f32 v[70:71], v[70:71], v[70:71]
	v_pk_mul_f32 v[72:73], v[66:67], v[66:67]
	v_pk_mul_f32 v[76:77], v[68:69], v[68:69]
	v_max_f32_e32 v58, v58, v58
	v_max_f32_e32 v59, v59, v59
	v_cvt_pk_bf16_f32 v66, v70, v71
	v_cvt_pk_bf16_f32 v67, v72, v73
	v_cvt_pk_bf16_f32 v68, v74, v75
	v_cvt_pk_bf16_f32 v69, v76, v77
	v_max_f32_e32 v58, 0, v58
	v_max_f32_e32 v59, 0, v59
	global_store_dwordx4 v[82:83], v[66:69], off offset:256
	v_max_f32_e32 v62, v62, v62
	v_max_f32_e32 v63, v63, v63
	v_pk_mul_f32 v[68:69], v[58:59], v[58:59]
	v_max_f32_e32 v59, v60, v60
	v_max_f32_e32 v62, 0, v62
	v_max_f32_e32 v63, 0, v63
	v_max_f32_e32 v58, v64, v64
	v_max_f32_e32 v60, 0, v59
	v_max_f32_e32 v59, v65, v65
	v_max_f32_e32 v61, v61, v61
	v_pk_mul_f32 v[62:63], v[62:63], v[62:63]
	v_max_f32_e32 v58, 0, v58
	v_max_f32_e32 v59, 0, v59
	v_max_f32_e32 v61, 0, v61
	s_mov_b32 s3, 0x200000
	v_pk_mul_f32 v[64:65], v[58:59], v[58:59]
	v_pk_mul_f32 v[70:71], v[60:61], v[60:61]
	v_cvt_pk_bf16_f32 v58, v62, v63
	v_add_co_u32_e32 v62, vcc, s3, v140
	v_max_f32_e32 v50, v50, v50
	v_max_f32_e32 v51, v51, v51
	v_cvt_pk_bf16_f32 v59, v64, v65
	v_cvt_pk_bf16_f32 v60, v68, v69
	v_cvt_pk_bf16_f32 v61, v70, v71
	v_addc_co_u32_e32 v63, vcc, 0, v141, vcc
	v_max_f32_e32 v50, 0, v50
	v_max_f32_e32 v51, 0, v51
	global_store_dwordx4 v[62:63], v[58:61], off
	v_max_f32_e32 v54, v54, v54
	v_max_f32_e32 v55, v55, v55
	v_pk_mul_f32 v[58:59], v[50:51], v[50:51]
	v_max_f32_e32 v51, v52, v52
	v_max_f32_e32 v50, v56, v56
	v_max_f32_e32 v52, 0, v51
	v_max_f32_e32 v51, v57, v57
	v_max_f32_e32 v53, v53, v53
	v_max_f32_e32 v54, 0, v54
	v_max_f32_e32 v55, 0, v55
	v_max_f32_e32 v50, 0, v50
	v_max_f32_e32 v51, 0, v51
	v_max_f32_e32 v53, 0, v53
	s_mov_b64 s[20:21], 0x200000
	v_pk_mul_f32 v[54:55], v[54:55], v[54:55]
	v_pk_mul_f32 v[56:57], v[50:51], v[50:51]
	v_pk_mul_f32 v[60:61], v[52:53], v[52:53]
	v_max_f32_e32 v42, v42, v42
	v_max_f32_e32 v43, v43, v43
	v_lshl_add_u64 v[66:67], v[140:141], 0, s[20:21]
	v_cvt_pk_bf16_f32 v50, v54, v55
	v_cvt_pk_bf16_f32 v51, v56, v57
	v_cvt_pk_bf16_f32 v52, v58, v59
	v_cvt_pk_bf16_f32 v53, v60, v61
	v_max_f32_e32 v42, 0, v42
	v_max_f32_e32 v43, 0, v43
	global_store_dwordx4 v[66:67], v[50:53], off offset:256
	v_max_f32_e32 v46, v46, v46
	v_max_f32_e32 v47, v47, v47
	v_pk_mul_f32 v[52:53], v[42:43], v[42:43]
	v_max_f32_e32 v43, v44, v44
	v_max_f32_e32 v46, 0, v46
	v_max_f32_e32 v47, 0, v47
	v_max_f32_e32 v42, v48, v48
	v_max_f32_e32 v44, 0, v43
	v_max_f32_e32 v43, v49, v49
	v_max_f32_e32 v45, v45, v45
	v_pk_mul_f32 v[46:47], v[46:47], v[46:47]
	v_max_f32_e32 v42, 0, v42
	v_max_f32_e32 v43, 0, v43
	v_max_f32_e32 v45, 0, v45
	s_mov_b32 s3, 0x240000
	v_pk_mul_f32 v[48:49], v[42:43], v[42:43]
	v_pk_mul_f32 v[54:55], v[44:45], v[44:45]
	v_cvt_pk_bf16_f32 v42, v46, v47
	v_add_co_u32_e32 v46, vcc, s3, v140
	v_max_f32_e32 v34, v34, v34
	v_max_f32_e32 v35, v35, v35
	v_cvt_pk_bf16_f32 v43, v48, v49
	v_cvt_pk_bf16_f32 v44, v52, v53
	v_cvt_pk_bf16_f32 v45, v54, v55
; __device__ __forceinline__ unsigned cvt_pk_bf16(float lo, float hi) { f32x2_t v = {lo, hi}; bf16x2_t b = __builtin_convertvector(v, bf16x2_t); return __builtin_bit_cast(unsigned, b); }
; #define PG8_WAIT_V(n) asm volatile("s_waitcnt vmcnt(" #n ")" ::: "memory")
; #define PG8_BAR __builtin_amdgcn_s_barrier()
; template <class Epi, class Sched>
; __device__ __forceinline__ void gemm_phase(LAS unsigned char* lds, const Gemm g, const Sched& S, const Epi& E) {
;     ...
;         if (!has_next) break;
; #pragma unroll
;         for (int a = 0; a < 2; ++a)
; #pragma unroll
;             for (int b = 0; b < 2; ++b)
; #pragma unroll
;                 for (int m = 0; m < 4; ++m)
; #pragma unroll
;                     for (int n = 0; n < 2; ++n) acc[a][b][m][n] = (f32x4){0.f, 0.f, 0.f, 0.f};
;         cur = nxt; cA = nA; cB = nB; ++ui;
;     }
;     PG8_WAIT_V(0);
;     if (wr == 0) PG8_BAR;
;     PG8_BAR;
;     __device__ __forceinline__ void operator()(const f32x4 (&acc)[2][2][4][2], const pg8::Unit& u, int wr, int wc, int fr, int fq) const {
;     ...
;             for (int m = 0; m < 4; ++m) { const int row = row0 + ai * 128 + m * 16; bf16_t* rowp = O + (size_t)row * ldc + col0;
; #pragma unroll
;                 for (int bj = 0; bj < 2; ++bj) { f32x4 v0 = acc[ai][bj][m][0], v1 = acc[ai][bj][m][1];
;                     if (ACT == 1) {
; #pragma unroll
;                         for (int j = 0; j < 4; ++j) { float a = fmaxf(v0[j], 0.f), b = fmaxf(v1[j], 0.f); v0[j] = a * a; v1[j] = b * b; } }
;                     if (ACT == 0) { if (u.pn == (C_G / 256) && bj == 0 && wc == 0 && fq < 2) { float* gp = gate + (size_t)row * 16 + 8 * fq; *(f32x4*)gp = v0; *(f32x4*)(gp + 4) = v1; } }
;                     u32x4 w; w.x = cvt_pk_bf16(v0[0], v0[1]); w.y = cvt_pk_bf16(v0[2], v0[3]); w.z = cvt_pk_bf16(v1[0], v1[1]); w.w = cvt_pk_bf16(v1[2], v1[3]);
;                     *(u32x4*)(rowp + bj * 128) = w; } }
	v_addc_co_u32_e32 v47, vcc, 0, v141, vcc
	v_max_f32_e32 v34, 0, v34
	v_max_f32_e32 v35, 0, v35
	global_store_dwordx4 v[46:47], v[42:45], off
	v_max_f32_e32 v38, v38, v38
	v_max_f32_e32 v39, v39, v39
	v_pk_mul_f32 v[42:43], v[34:35], v[34:35]
	v_max_f32_e32 v35, v36, v36
	v_max_f32_e32 v34, v40, v40
	v_max_f32_e32 v36, 0, v35
	v_max_f32_e32 v35, v41, v41
	v_max_f32_e32 v37, v37, v37
	v_max_f32_e32 v38, 0, v38
	v_max_f32_e32 v39, 0, v39
	v_max_f32_e32 v34, 0, v34
	v_max_f32_e32 v35, 0, v35
	v_max_f32_e32 v37, 0, v37
	s_mov_b64 s[20:21], 0x240000
	v_pk_mul_f32 v[38:39], v[38:39], v[38:39]
	v_pk_mul_f32 v[40:41], v[34:35], v[34:35]
	v_pk_mul_f32 v[44:45], v[36:37], v[36:37]
	v_max_f32_e32 v26, v26, v26
	v_max_f32_e32 v27, v27, v27
	v_lshl_add_u64 v[50:51], v[140:141], 0, s[20:21]
	v_cvt_pk_bf16_f32 v34, v38, v39
	v_cvt_pk_bf16_f32 v35, v40, v41
	v_cvt_pk_bf16_f32 v36, v42, v43
	v_cvt_pk_bf16_f32 v37, v44, v45
	v_max_f32_e32 v26, 0, v26
	v_max_f32_e32 v27, 0, v27
	global_store_dwordx4 v[50:51], v[34:37], off offset:256
	v_max_f32_e32 v30, v30, v30
	v_max_f32_e32 v31, v31, v31
	v_pk_mul_f32 v[36:37], v[26:27], v[26:27]
	v_max_f32_e32 v27, v28, v28
	v_max_f32_e32 v30, 0, v30
	v_max_f32_e32 v31, 0, v31
	v_max_f32_e32 v26, v32, v32
	v_max_f32_e32 v28, 0, v27
	v_max_f32_e32 v27, v33, v33
	v_max_f32_e32 v29, v29, v29
	v_pk_mul_f32 v[30:31], v[30:31], v[30:31]
	v_max_f32_e32 v26, 0, v26
	v_max_f32_e32 v27, 0, v27
	v_max_f32_e32 v29, 0, v29
	s_mov_b32 s3, 0x280000
	v_pk_mul_f32 v[32:33], v[26:27], v[26:27]
	v_pk_mul_f32 v[38:39], v[28:29], v[28:29]
	v_cvt_pk_bf16_f32 v26, v30, v31
	v_add_co_u32_e32 v30, vcc, s3, v140
	v_max_f32_e32 v18, v18, v18
	v_max_f32_e32 v19, v19, v19
	v_cvt_pk_bf16_f32 v27, v32, v33
	v_cvt_pk_bf16_f32 v28, v36, v37
	v_cvt_pk_bf16_f32 v29, v38, v39
	v_addc_co_u32_e32 v31, vcc, 0, v141, vcc
	v_max_f32_e32 v18, 0, v18
	v_max_f32_e32 v19, 0, v19
	global_store_dwordx4 v[30:31], v[26:29], off
	v_max_f32_e32 v22, v22, v22
	v_max_f32_e32 v23, v23, v23
	v_pk_mul_f32 v[26:27], v[18:19], v[18:19]
	v_max_f32_e32 v19, v20, v20
	v_max_f32_e32 v18, v24, v24
	v_max_f32_e32 v20, 0, v19
	v_max_f32_e32 v19, v25, v25
	v_max_f32_e32 v21, v21, v21
	v_max_f32_e32 v22, 0, v22
	v_max_f32_e32 v23, 0, v23
	v_max_f32_e32 v18, 0, v18
	v_max_f32_e32 v19, 0, v19
	v_max_f32_e32 v21, 0, v21
	s_mov_b64 s[20:21], 0x280000
	v_pk_mul_f32 v[22:23], v[22:23], v[22:23]
	v_pk_mul_f32 v[24:25], v[18:19], v[18:19]
	v_pk_mul_f32 v[28:29], v[20:21], v[20:21]
	v_max_f32_e32 v10, v10, v10
	v_max_f32_e32 v11, v11, v11
	v_lshl_add_u64 v[34:35], v[140:141], 0, s[20:21]
	v_cvt_pk_bf16_f32 v18, v22, v23
	v_cvt_pk_bf16_f32 v19, v24, v25
	v_cvt_pk_bf16_f32 v20, v26, v27
	v_cvt_pk_bf16_f32 v21, v28, v29
	v_max_f32_e32 v10, 0, v10
	v_max_f32_e32 v11, 0, v11
	global_store_dwordx4 v[34:35], v[18:21], off offset:256
	v_max_f32_e32 v14, v14, v14
	v_max_f32_e32 v15, v15, v15
	v_pk_mul_f32 v[20:21], v[10:11], v[10:11]
	v_max_f32_e32 v11, v12, v12
	v_max_f32_e32 v14, 0, v14
	v_max_f32_e32 v15, 0, v15
	v_max_f32_e32 v10, v16, v16
	v_max_f32_e32 v12, 0, v11
	v_max_f32_e32 v11, v17, v17
	v_max_f32_e32 v13, v13, v13
	v_pk_mul_f32 v[14:15], v[14:15], v[14:15]
	v_max_f32_e32 v10, 0, v10
	v_max_f32_e32 v11, 0, v11
	v_max_f32_e32 v13, 0, v13
	s_mov_b32 s3, 0x2c0000
	v_pk_mul_f32 v[16:17], v[10:11], v[10:11]
	v_pk_mul_f32 v[22:23], v[12:13], v[12:13]
	v_cvt_pk_bf16_f32 v10, v14, v15
	v_add_co_u32_e32 v14, vcc, s3, v140
	v_max_f32_e32 v2, v2, v2
	v_max_f32_e32 v3, v3, v3
	v_cvt_pk_bf16_f32 v11, v16, v17
	v_cvt_pk_bf16_f32 v12, v20, v21
	v_cvt_pk_bf16_f32 v13, v22, v23
	v_addc_co_u32_e32 v15, vcc, 0, v141, vcc
	v_max_f32_e32 v2, 0, v2
	v_max_f32_e32 v3, 0, v3
	global_store_dwordx4 v[14:15], v[10:13], off
	v_max_f32_e32 v6, v6, v6
	v_max_f32_e32 v7, v7, v7
	v_pk_mul_f32 v[10:11], v[2:3], v[2:3]
	v_max_f32_e32 v3, v4, v4
	v_max_f32_e32 v2, v8, v8
	v_max_f32_e32 v4, 0, v3
	v_max_f32_e32 v3, v9, v9
	v_max_f32_e32 v5, v5, v5
	v_max_f32_e32 v6, 0, v6
	v_max_f32_e32 v7, 0, v7
	v_max_f32_e32 v2, 0, v2
	v_max_f32_e32 v3, 0, v3
	v_max_f32_e32 v5, 0, v5
	s_mov_b64 s[20:21], 0x2c0000
	v_pk_mul_f32 v[6:7], v[6:7], v[6:7]
	v_pk_mul_f32 v[8:9], v[2:3], v[2:3]
	v_pk_mul_f32 v[12:13], v[4:5], v[4:5]
	v_lshl_add_u64 v[18:19], v[140:141], 0, s[20:21]
	v_cvt_pk_bf16_f32 v2, v6, v7
	v_cvt_pk_bf16_f32 v3, v8, v9
	v_cvt_pk_bf16_f32 v4, v10, v11
	v_cvt_pk_bf16_f32 v5, v12, v13
	s_and_b64 vcc, exec, s[0:1]
	s_mov_b32 s16, s8
	s_mov_b32 s18, s10
	s_mov_b64 s[22:23], s[14:15]
	s_mov_b64 s[20:21], s[12:13]
	global_store_dwordx4 v[18:19], v[2:5], off offset:256
	s_cbranch_vccz .LBB0_1276
	s_waitcnt vmcnt(0)
	s_cmpk_gt_u32 s27, 0xff
	s_cbranch_scc1 .LBB0_1283
	s_barrier
